# cmp_finish: w2 shared through LDS (one LDS-DMA copy per workgroup, +16KB static LDS); flat dwordx4 stores -> global; topk without extra SGPRs
# speedup vs baseline: 1.0364x; 1.0127x over previous
.LBB0_156:
	v_add_u32_e32 v4, s4, v4
	v_cmp_lt_i32_e32 vcc, s5, v4
	global_store_dwordx4 v[6:7], v[0:3], off
	s_or_b64 s[6:7], vcc, s[6:7]
	v_lshl_add_u64 v[6:7], v[6:7], 0, s[0:1]
	s_andn2_b64 exec, exec, s[6:7]
	s_cbranch_execnz .LBB0_156

.LBB0_227:
	v_lshl_or_b32 v146, s57, 8, v150
	v_lshl_add_u32 v156, s28, 8, v148
	v_ashrrev_i32_e32 v147, 31, v146
	v_mov_b64_e32 v[144:145], s[4:5]
	v_mad_i64_i32 v[154:155], s[30:31], v156, s56, v[144:145]
	v_lshlrev_b64 v[146:147], 1, v[146:147]
	v_lshl_add_u64 v[154:155], v[154:155], 0, v[146:147]
	v_cvt_pk_bf16_f32 v124, v124, v125
	v_cvt_pk_bf16_f32 v125, v126, v127
	v_cvt_pk_bf16_f32 v126, v120, v121
	v_cvt_pk_bf16_f32 v127, v122, v123
	global_store_dwordx4 v[154:155], v[124:127], off
	v_cvt_pk_bf16_f32 v112, v112, v113
	v_cvt_pk_bf16_f32 v113, v114, v115
	v_cvt_pk_bf16_f32 v114, v104, v105
	v_or_b32_e32 v104, 16, v156
	v_mad_i64_i32 v[104:105], s[30:31], v104, s56, v[144:145]
	v_cvt_pk_bf16_f32 v115, v106, v107
	global_store_dwordx4 v[154:155], v[112:115], off offset:256
	s_andn2_b64 vcc, exec, s[6:7]
	s_mov_b64 s[6:7], -1
	v_lshl_add_u64 v[112:113], v[104:105], 0, v[146:147]
	v_cvt_pk_bf16_f32 v104, v116, v117
	v_cvt_pk_bf16_f32 v105, v118, v119
	v_cvt_pk_bf16_f32 v106, v108, v109
	v_cvt_pk_bf16_f32 v107, v110, v111
	global_store_dwordx4 v[112:113], v[104:107], off
	v_cvt_pk_bf16_f32 v96, v96, v97
	v_cvt_pk_bf16_f32 v97, v98, v99
	v_cvt_pk_bf16_f32 v98, v88, v89
	v_or_b32_e32 v88, 32, v156
	v_mad_i64_i32 v[88:89], s[30:31], v88, s56, v[144:145]
	v_cvt_pk_bf16_f32 v99, v90, v91
	global_store_dwordx4 v[112:113], v[96:99], off offset:256
	s_nop 1
	v_lshl_add_u64 v[96:97], v[88:89], 0, v[146:147]
	v_cvt_pk_bf16_f32 v88, v100, v101
	v_cvt_pk_bf16_f32 v89, v102, v103
	v_cvt_pk_bf16_f32 v90, v92, v93
	v_cvt_pk_bf16_f32 v91, v94, v95
	global_store_dwordx4 v[96:97], v[88:91], off
	v_cvt_pk_bf16_f32 v80, v80, v81
	v_cvt_pk_bf16_f32 v81, v82, v83
	v_cvt_pk_bf16_f32 v82, v72, v73
	v_or_b32_e32 v72, 48, v156
	v_mad_i64_i32 v[72:73], s[30:31], v72, s56, v[144:145]
	v_cvt_pk_bf16_f32 v83, v74, v75
	global_store_dwordx4 v[96:97], v[80:83], off offset:256
	s_nop 1
	v_lshl_add_u64 v[80:81], v[72:73], 0, v[146:147]
	v_cvt_pk_bf16_f32 v72, v84, v85
	v_cvt_pk_bf16_f32 v73, v86, v87
	v_cvt_pk_bf16_f32 v74, v76, v77
	v_cvt_pk_bf16_f32 v75, v78, v79
	global_store_dwordx4 v[80:81], v[72:75], off
	v_cvt_pk_bf16_f32 v68, v68, v69
	v_cvt_pk_bf16_f32 v69, v70, v71
	v_cvt_pk_bf16_f32 v70, v64, v65
	v_add_u32_e32 v64, 0x80, v156
	v_mad_i64_i32 v[64:65], s[30:31], v64, s56, v[144:145]
	v_lshl_add_u64 v[64:65], v[64:65], 0, v[146:147]
	v_cvt_pk_bf16_f32 v71, v66, v67
	global_store_dwordx4 v[80:81], v[68:71], off offset:256
	v_cvt_pk_bf16_f32 v60, v60, v61
	v_cvt_pk_bf16_f32 v61, v62, v63
	v_cvt_pk_bf16_f32 v62, v56, v57
	v_cvt_pk_bf16_f32 v63, v58, v59
	global_store_dwordx4 v[64:65], v[60:63], off
	v_cvt_pk_bf16_f32 v48, v48, v49
	v_cvt_pk_bf16_f32 v49, v50, v51
	v_cvt_pk_bf16_f32 v50, v40, v41
	v_add_u32_e32 v40, 0x90, v156
	v_mad_i64_i32 v[40:41], s[30:31], v40, s56, v[144:145]
	v_cvt_pk_bf16_f32 v51, v42, v43
	global_store_dwordx4 v[64:65], v[48:51], off offset:256
	s_nop 1
	v_lshl_add_u64 v[48:49], v[40:41], 0, v[146:147]
	v_cvt_pk_bf16_f32 v40, v52, v53
	v_cvt_pk_bf16_f32 v41, v54, v55
	v_cvt_pk_bf16_f32 v42, v44, v45
	v_cvt_pk_bf16_f32 v43, v46, v47
	global_store_dwordx4 v[48:49], v[40:43], off
	v_cvt_pk_bf16_f32 v32, v32, v33
	v_cvt_pk_bf16_f32 v33, v34, v35
	v_cvt_pk_bf16_f32 v34, v24, v25
	v_add_u32_e32 v24, 0xa0, v156
	v_mad_i64_i32 v[24:25], s[30:31], v24, s56, v[144:145]
	v_cvt_pk_bf16_f32 v35, v26, v27
	global_store_dwordx4 v[48:49], v[32:35], off offset:256
	s_nop 1
	v_lshl_add_u64 v[32:33], v[24:25], 0, v[146:147]
	v_cvt_pk_bf16_f32 v24, v36, v37
	v_cvt_pk_bf16_f32 v25, v38, v39
	v_cvt_pk_bf16_f32 v26, v28, v29
	v_cvt_pk_bf16_f32 v27, v30, v31
	global_store_dwordx4 v[32:33], v[24:27], off
	v_cvt_pk_bf16_f32 v16, v16, v17
	v_cvt_pk_bf16_f32 v17, v18, v19
	v_cvt_pk_bf16_f32 v18, v8, v9
	v_add_u32_e32 v8, 0xb0, v156
	v_mad_i64_i32 v[8:9], s[30:31], v8, s56, v[144:145]
	v_cvt_pk_bf16_f32 v19, v10, v11
	global_store_dwordx4 v[32:33], v[16:19], off offset:256
	s_nop 1
	v_lshl_add_u64 v[16:17], v[8:9], 0, v[146:147]
	v_cvt_pk_bf16_f32 v8, v20, v21
	v_cvt_pk_bf16_f32 v9, v22, v23
	v_cvt_pk_bf16_f32 v10, v12, v13
	v_cvt_pk_bf16_f32 v11, v14, v15
	global_store_dwordx4 v[16:17], v[8:11], off
	v_cvt_pk_bf16_f32 v4, v4, v5
	v_cvt_pk_bf16_f32 v5, v6, v7
	v_cvt_pk_bf16_f32 v6, v0, v1
	v_cvt_pk_bf16_f32 v7, v2, v3
	global_store_dwordx4 v[16:17], v[4:7], off offset:256
	s_cbranch_vccnz .LBB0_220
	s_andn2_b64 vcc, exec, s[2:3]
	s_cbranch_vccnz .LBB0_219
	s_barrier
	s_branch .LBB0_219

.LBB0_365:
	ds_read_b128 v[20:23], v16
	ds_read_b128 v[24:27], v16 offset:1024
	ds_read_b128 v[28:31], v16 offset:2048
	ds_read_b128 v[32:35], v16 offset:3072
	ds_read_b128 v[36:39], v17
	ds_read_b128 v[40:43], v17 offset:1024
	ds_read_b128 v[44:47], v17 offset:2048
	ds_read_b128 v[48:51], v17 offset:3072
	s_add_u32 s30, s33, s26
	s_addc_u32 s31, s42, s27
	s_and_b64 s[34:35], s[2:3], exec
	s_cselect_b32 s41, s31, s37
	s_cselect_b32 s40, s30, s36
	s_add_u32 s34, s43, s28
	s_addc_u32 s35, s44, s29
	s_and_b64 s[2:3], s[2:3], exec
	s_cselect_b32 s3, s35, s39
	s_cselect_b32 s2, s34, s38
	s_add_u32 s64, s36, 0x40080
	s_addc_u32 s65, s37, 0
	s_add_i32 s70, s45, 0xc000
	v_lshl_add_u64 v[84:85], s[64:65], 0, v[6:7]
	s_mov_b32 m0, s70
	ds_read_b128 v[52:55], v18
	ds_read_b128 v[56:59], v18 offset:1024
	ds_read_b128 v[60:63], v18 offset:2048
	ds_read_b128 v[64:67], v18 offset:3072
	ds_read_b128 v[68:71], v18 offset:4096
	ds_read_b128 v[72:75], v18 offset:5120
	ds_read_b128 v[76:79], v18 offset:6144
	ds_read_b128 v[80:83], v18 offset:7168
	global_load_lds_dwordx4 v[84:85], off
	v_lshl_add_u64 v[84:85], s[64:65], 0, v[2:3]
	s_add_i32 s64, s45, 0xe000
	s_mov_b32 m0, s64
	s_nop 0
	global_load_lds_dwordx4 v[84:85], off
	s_waitcnt vmcnt(8)
	s_waitcnt lgkmcnt(0)
	s_barrier
	s_setprio 1
	s_waitcnt lgkmcnt(0)
	v_mfma_f32_16x16x32_bf16 v[84:87], v[20:23], v[52:55], 0
	v_mfma_f32_16x16x32_bf16 v[88:91], v[28:31], v[52:55], 0
	v_mfma_f32_16x16x32_bf16 v[92:95], v[20:23], v[60:63], 0
	v_mfma_f32_16x16x32_bf16 v[96:99], v[28:31], v[60:63], 0
	v_mfma_f32_16x16x32_bf16 v[100:103], v[20:23], v[68:71], 0
	v_mfma_f32_16x16x32_bf16 v[104:107], v[28:31], v[68:71], 0
	v_mfma_f32_16x16x32_bf16 v[108:111], v[20:23], v[76:79], 0
	v_mfma_f32_16x16x32_bf16 v[112:115], v[28:31], v[76:79], 0
	v_mfma_f32_16x16x32_bf16 v[84:87], v[24:27], v[56:59], v[84:87]
	v_mfma_f32_16x16x32_bf16 v[88:91], v[32:35], v[56:59], v[88:91]
	v_mfma_f32_16x16x32_bf16 v[92:95], v[24:27], v[64:67], v[92:95]
	v_mfma_f32_16x16x32_bf16 v[96:99], v[32:35], v[64:67], v[96:99]
	v_mfma_f32_16x16x32_bf16 v[100:103], v[24:27], v[72:75], v[100:103]
	v_mfma_f32_16x16x32_bf16 v[104:107], v[32:35], v[72:75], v[104:107]
	v_mfma_f32_16x16x32_bf16 v[108:111], v[24:27], v[80:83], v[108:111]
	v_mfma_f32_16x16x32_bf16 v[112:115], v[32:35], v[80:83], v[112:115]
	s_setprio 0
	s_setprio 1
	v_mfma_f32_16x16x32_bf16 v[116:119], v[36:39], v[52:55], 0
	v_mfma_f32_16x16x32_bf16 v[52:55], v[44:47], v[52:55], 0
	v_mfma_f32_16x16x32_bf16 v[116:119], v[40:43], v[56:59], v[116:119]
	v_mfma_f32_16x16x32_bf16 v[52:55], v[48:51], v[56:59], v[52:55]
	v_mfma_f32_16x16x32_bf16 v[56:59], v[36:39], v[60:63], 0
	v_mfma_f32_16x16x32_bf16 v[60:63], v[44:47], v[60:63], 0
	v_mfma_f32_16x16x32_bf16 v[56:59], v[40:43], v[64:67], v[56:59]
	v_mfma_f32_16x16x32_bf16 v[60:63], v[48:51], v[64:67], v[60:63]
	v_mfma_f32_16x16x32_bf16 v[64:67], v[36:39], v[68:71], 0
	v_mfma_f32_16x16x32_bf16 v[68:71], v[44:47], v[68:71], 0
	v_mfma_f32_16x16x32_bf16 v[64:67], v[40:43], v[72:75], v[64:67]
	v_mfma_f32_16x16x32_bf16 v[68:71], v[48:51], v[72:75], v[68:71]
	v_mfma_f32_16x16x32_bf16 v[72:75], v[36:39], v[76:79], 0
	v_mfma_f32_16x16x32_bf16 v[76:79], v[44:47], v[76:79], 0
	v_mfma_f32_16x16x32_bf16 v[72:75], v[40:43], v[80:83], v[72:75]
	v_mfma_f32_16x16x32_bf16 v[76:79], v[48:51], v[80:83], v[76:79]
	s_setprio 0
	s_barrier
	v_readlane_b32 s78, v247, 11
	s_add_i32 s68, s57, s78
	v_lshl_add_u64 v[212:213], s[38:39], 0, v[4:5]
	s_add_i32 s65, s68, 0x2000
	v_lshl_add_u64 v[148:149], v[212:213], 0, s[8:9]
	s_mov_b32 m0, s68
	v_lshl_add_u64 v[214:215], s[38:39], 0, v[0:1]
	s_add_u32 s72, s38, 0x80100
	ds_read_b128 v[80:83], v18 offset:16384
	ds_read_b128 v[120:123], v18 offset:17408
	ds_read_b128 v[124:127], v18 offset:18432
	ds_read_b128 v[128:131], v18 offset:19456
	ds_read_b128 v[132:135], v18 offset:20480
	ds_read_b128 v[136:139], v18 offset:21504
	ds_read_b128 v[140:143], v18 offset:22528
	ds_read_b128 v[144:147], v18 offset:23552
	global_load_lds_dwordx4 v[148:149], off
	v_lshl_add_u64 v[148:149], v[214:215], 0, s[8:9]
	s_mov_b32 m0, s65
	s_addc_u32 s73, s39, 0
	s_add_i32 s66, s58, s78
	global_load_lds_dwordx4 v[148:149], off
	v_lshl_add_u64 v[148:149], s[72:73], 0, v[4:5]
	s_mov_b32 m0, s66
	s_add_i32 s67, s66, 0x2000
	global_load_lds_dwordx4 v[148:149], off
	v_lshl_add_u64 v[148:149], s[72:73], 0, v[0:1]
	s_mov_b32 m0, s67
	v_lshl_add_u64 v[216:217], s[36:37], 0, v[6:7]
	global_load_lds_dwordx4 v[148:149], off
	v_lshl_add_u64 v[148:149], v[216:217], 0, s[8:9]
	s_mov_b32 m0, s45
	v_lshl_add_u64 v[218:219], s[36:37], 0, v[2:3]
	global_load_lds_dwordx4 v[148:149], off
	v_lshl_add_u64 v[148:149], v[218:219], 0, s[8:9]
	s_mov_b32 m0, s46
	s_nop 0
	global_load_lds_dwordx4 v[148:149], off
	s_waitcnt vmcnt(8)
	s_waitcnt lgkmcnt(0)
	s_barrier
	s_setprio 1
	s_waitcnt lgkmcnt(0)
	v_mfma_f32_16x16x32_bf16 v[148:151], v[20:23], v[80:83], 0
	v_mfma_f32_16x16x32_bf16 v[156:159], v[20:23], v[124:127], 0
	v_mfma_f32_16x16x32_bf16 v[164:167], v[20:23], v[132:135], 0
	v_mfma_f32_16x16x32_bf16 v[20:23], v[20:23], v[140:143], 0
	v_mfma_f32_16x16x32_bf16 v[148:151], v[24:27], v[120:123], v[148:151]
	v_mfma_f32_16x16x32_bf16 v[152:155], v[28:31], v[80:83], 0
	v_mfma_f32_16x16x32_bf16 v[156:159], v[24:27], v[128:131], v[156:159]
	v_mfma_f32_16x16x32_bf16 v[160:163], v[28:31], v[124:127], 0
	v_mfma_f32_16x16x32_bf16 v[164:167], v[24:27], v[136:139], v[164:167]
	v_mfma_f32_16x16x32_bf16 v[168:171], v[28:31], v[132:135], 0
	v_mfma_f32_16x16x32_bf16 v[20:23], v[24:27], v[144:147], v[20:23]
	v_mfma_f32_16x16x32_bf16 v[24:27], v[28:31], v[140:143], 0
	v_mfma_f32_16x16x32_bf16 v[152:155], v[32:35], v[120:123], v[152:155]
	v_mfma_f32_16x16x32_bf16 v[160:163], v[32:35], v[128:131], v[160:163]
	v_mfma_f32_16x16x32_bf16 v[168:171], v[32:35], v[136:139], v[168:171]
	v_mfma_f32_16x16x32_bf16 v[24:27], v[32:35], v[144:147], v[24:27]
	s_setprio 0
	s_setprio 1
	v_mfma_f32_16x16x32_bf16 v[28:31], v[36:39], v[80:83], 0
	v_mfma_f32_16x16x32_bf16 v[32:35], v[44:47], v[80:83], 0
	v_mfma_f32_16x16x32_bf16 v[28:31], v[40:43], v[120:123], v[28:31]
	v_mfma_f32_16x16x32_bf16 v[32:35], v[48:51], v[120:123], v[32:35]
	v_mfma_f32_16x16x32_bf16 v[80:83], v[36:39], v[124:127], 0
	v_mfma_f32_16x16x32_bf16 v[120:123], v[44:47], v[124:127], 0
	v_mfma_f32_16x16x32_bf16 v[124:127], v[36:39], v[132:135], 0
	v_mfma_f32_16x16x32_bf16 v[36:39], v[36:39], v[140:143], 0
	v_mfma_f32_16x16x32_bf16 v[80:83], v[40:43], v[128:131], v[80:83]
	v_mfma_f32_16x16x32_bf16 v[120:123], v[48:51], v[128:131], v[120:123]
	v_mfma_f32_16x16x32_bf16 v[124:127], v[40:43], v[136:139], v[124:127]
	v_mfma_f32_16x16x32_bf16 v[128:131], v[44:47], v[132:135], 0
	v_mfma_f32_16x16x32_bf16 v[36:39], v[40:43], v[144:147], v[36:39]
	v_mfma_f32_16x16x32_bf16 v[40:43], v[44:47], v[140:143], 0
	v_mfma_f32_16x16x32_bf16 v[128:131], v[48:51], v[136:139], v[128:131]
	v_mfma_f32_16x16x32_bf16 v[40:43], v[48:51], v[144:147], v[40:43]
	s_setprio 0
	s_barrier
	s_add_i32 s71, 0, 0x18000
	s_add_i32 s74, 0, 0x1c000
	v_add_u32_e32 v19, s71, v15
	v_add_u32_e32 v222, s74, v15
	ds_read_b128 v[44:47], v19
	ds_read_b128 v[48:51], v19 offset:1024
	ds_read_b128 v[132:135], v19 offset:2048
	ds_read_b128 v[136:139], v19 offset:3072
	ds_read_b128 v[140:143], v222
	ds_read_b128 v[144:147], v222 offset:1024
	ds_read_b128 v[172:175], v222 offset:2048
	ds_read_b128 v[176:179], v222 offset:3072
	s_add_u32 s72, s36, 0x40100
	s_addc_u32 s73, s37, 0
	s_mov_b32 m0, s47
	v_lshl_add_u64 v[220:221], s[72:73], 0, v[6:7]
	ds_read_b128 v[180:183], v18 offset:32768
	ds_read_b128 v[184:187], v18 offset:33792
	ds_read_b128 v[188:191], v18 offset:34816
	ds_read_b128 v[192:195], v18 offset:35840
	ds_read_b128 v[196:199], v18 offset:36864
	ds_read_b128 v[200:203], v18 offset:37888
	ds_read_b128 v[204:207], v18 offset:38912
	ds_read_b128 v[208:211], v18 offset:39936
	global_load_lds_dwordx4 v[220:221], off
	v_lshl_add_u64 v[220:221], s[72:73], 0, v[2:3]
	s_mov_b32 m0, s48
	s_nop 0
	global_load_lds_dwordx4 v[220:221], off
	s_waitcnt vmcnt(8)
	s_waitcnt lgkmcnt(0)
	s_barrier
	s_setprio 1
	s_waitcnt lgkmcnt(0)
	v_mfma_f32_16x16x32_bf16 v[84:87], v[44:47], v[180:183], v[84:87]
	v_mfma_f32_16x16x32_bf16 v[88:91], v[132:135], v[180:183], v[88:91]
	v_mfma_f32_16x16x32_bf16 v[92:95], v[44:47], v[188:191], v[92:95]
	v_mfma_f32_16x16x32_bf16 v[96:99], v[132:135], v[188:191], v[96:99]
	v_mfma_f32_16x16x32_bf16 v[100:103], v[44:47], v[196:199], v[100:103]
	v_mfma_f32_16x16x32_bf16 v[104:107], v[132:135], v[196:199], v[104:107]
	v_mfma_f32_16x16x32_bf16 v[108:111], v[44:47], v[204:207], v[108:111]
	v_mfma_f32_16x16x32_bf16 v[112:115], v[132:135], v[204:207], v[112:115]
	v_mfma_f32_16x16x32_bf16 v[84:87], v[48:51], v[184:187], v[84:87]
	v_mfma_f32_16x16x32_bf16 v[88:91], v[136:139], v[184:187], v[88:91]
	v_mfma_f32_16x16x32_bf16 v[92:95], v[48:51], v[192:195], v[92:95]
	v_mfma_f32_16x16x32_bf16 v[96:99], v[136:139], v[192:195], v[96:99]
	v_mfma_f32_16x16x32_bf16 v[100:103], v[48:51], v[200:203], v[100:103]
	v_mfma_f32_16x16x32_bf16 v[104:107], v[136:139], v[200:203], v[104:107]
	v_mfma_f32_16x16x32_bf16 v[108:111], v[48:51], v[208:211], v[108:111]
	v_mfma_f32_16x16x32_bf16 v[112:115], v[136:139], v[208:211], v[112:115]
	s_setprio 0
	s_setprio 1
	v_mfma_f32_16x16x32_bf16 v[116:119], v[140:143], v[180:183], v[116:119]
	v_mfma_f32_16x16x32_bf16 v[52:55], v[172:175], v[180:183], v[52:55]
	v_mfma_f32_16x16x32_bf16 v[56:59], v[140:143], v[188:191], v[56:59]
	v_mfma_f32_16x16x32_bf16 v[60:63], v[172:175], v[188:191], v[60:63]
	v_mfma_f32_16x16x32_bf16 v[64:67], v[140:143], v[196:199], v[64:67]
	v_mfma_f32_16x16x32_bf16 v[68:71], v[172:175], v[196:199], v[68:71]
	v_mfma_f32_16x16x32_bf16 v[72:75], v[140:143], v[204:207], v[72:75]
	v_mfma_f32_16x16x32_bf16 v[76:79], v[172:175], v[204:207], v[76:79]
	v_mfma_f32_16x16x32_bf16 v[116:119], v[144:147], v[184:187], v[116:119]
	v_mfma_f32_16x16x32_bf16 v[52:55], v[176:179], v[184:187], v[52:55]
	v_mfma_f32_16x16x32_bf16 v[56:59], v[144:147], v[192:195], v[56:59]
	v_mfma_f32_16x16x32_bf16 v[60:63], v[176:179], v[192:195], v[60:63]
	v_mfma_f32_16x16x32_bf16 v[64:67], v[144:147], v[200:203], v[64:67]
	v_mfma_f32_16x16x32_bf16 v[68:71], v[176:179], v[200:203], v[68:71]
	v_mfma_f32_16x16x32_bf16 v[72:75], v[144:147], v[208:211], v[72:75]
	v_mfma_f32_16x16x32_bf16 v[76:79], v[176:179], v[208:211], v[76:79]
	s_setprio 0
	s_barrier
	s_add_i32 s71, s71, s78
	s_add_i32 s69, s71, 0x2000
	v_lshl_add_u64 v[212:213], v[212:213], 0, s[10:11]
	s_mov_b32 m0, s71
	s_add_u32 s72, s38, 0x80180
	ds_read_b128 v[180:183], v18 offset:49152
	ds_read_b128 v[184:187], v18 offset:50176
	ds_read_b128 v[188:191], v18 offset:51200
	ds_read_b128 v[192:195], v18 offset:52224
	ds_read_b128 v[196:199], v18 offset:53248
	ds_read_b128 v[200:203], v18 offset:54272
	ds_read_b128 v[204:207], v18 offset:55296
	ds_read_b128 v[208:211], v18 offset:56320
	global_load_lds_dwordx4 v[212:213], off
	v_lshl_add_u64 v[212:213], v[214:215], 0, s[10:11]
	s_mov_b32 m0, s69
	s_addc_u32 s73, s39, 0
	s_add_i32 s38, s74, s78
	global_load_lds_dwordx4 v[212:213], off
	v_lshl_add_u64 v[212:213], s[72:73], 0, v[4:5]
	s_mov_b32 m0, s38
	s_add_i32 s39, s38, 0x2000
	global_load_lds_dwordx4 v[212:213], off
	v_lshl_add_u64 v[212:213], s[72:73], 0, v[0:1]
	s_mov_b32 m0, s39
	s_nop 0
	global_load_lds_dwordx4 v[212:213], off
	v_lshl_add_u64 v[212:213], v[216:217], 0, s[10:11]
	s_mov_b32 m0, s52
	s_nop 0
	global_load_lds_dwordx4 v[212:213], off
	v_lshl_add_u64 v[212:213], v[218:219], 0, s[10:11]
	s_mov_b32 m0, s53
	s_nop 0
	global_load_lds_dwordx4 v[212:213], off
	s_waitcnt vmcnt(8)
	s_waitcnt lgkmcnt(0)
	s_barrier
	s_setprio 1
	s_waitcnt lgkmcnt(0)
	v_mfma_f32_16x16x32_bf16 v[148:151], v[44:47], v[180:183], v[148:151]
	v_mfma_f32_16x16x32_bf16 v[152:155], v[132:135], v[180:183], v[152:155]
	v_mfma_f32_16x16x32_bf16 v[156:159], v[44:47], v[188:191], v[156:159]
	v_mfma_f32_16x16x32_bf16 v[160:163], v[132:135], v[188:191], v[160:163]
	v_mfma_f32_16x16x32_bf16 v[164:167], v[44:47], v[196:199], v[164:167]
	v_mfma_f32_16x16x32_bf16 v[168:171], v[132:135], v[196:199], v[168:171]
	v_mfma_f32_16x16x32_bf16 v[20:23], v[44:47], v[204:207], v[20:23]
	v_mfma_f32_16x16x32_bf16 v[24:27], v[132:135], v[204:207], v[24:27]
	v_mfma_f32_16x16x32_bf16 v[148:151], v[48:51], v[184:187], v[148:151]
	v_mfma_f32_16x16x32_bf16 v[152:155], v[136:139], v[184:187], v[152:155]
	v_mfma_f32_16x16x32_bf16 v[156:159], v[48:51], v[192:195], v[156:159]
	v_mfma_f32_16x16x32_bf16 v[160:163], v[136:139], v[192:195], v[160:163]
	v_mfma_f32_16x16x32_bf16 v[164:167], v[48:51], v[200:203], v[164:167]
	v_mfma_f32_16x16x32_bf16 v[168:171], v[136:139], v[200:203], v[168:171]
	v_mfma_f32_16x16x32_bf16 v[20:23], v[48:51], v[208:211], v[20:23]
	v_mfma_f32_16x16x32_bf16 v[24:27], v[136:139], v[208:211], v[24:27]
	s_setprio 0
	s_setprio 1
	v_mfma_f32_16x16x32_bf16 v[28:31], v[140:143], v[180:183], v[28:31]
	v_mfma_f32_16x16x32_bf16 v[32:35], v[172:175], v[180:183], v[32:35]
	v_mfma_f32_16x16x32_bf16 v[44:47], v[140:143], v[188:191], v[80:83]
	v_mfma_f32_16x16x32_bf16 v[48:51], v[172:175], v[188:191], v[120:123]
	v_mfma_f32_16x16x32_bf16 v[80:83], v[140:143], v[196:199], v[124:127]
	v_mfma_f32_16x16x32_bf16 v[120:123], v[172:175], v[196:199], v[128:131]
	v_mfma_f32_16x16x32_bf16 v[36:39], v[140:143], v[204:207], v[36:39]
	v_mfma_f32_16x16x32_bf16 v[40:43], v[172:175], v[204:207], v[40:43]
	v_mfma_f32_16x16x32_bf16 v[28:31], v[144:147], v[184:187], v[28:31]
	v_mfma_f32_16x16x32_bf16 v[32:35], v[176:179], v[184:187], v[32:35]
	v_mfma_f32_16x16x32_bf16 v[44:47], v[144:147], v[192:195], v[44:47]
	v_mfma_f32_16x16x32_bf16 v[48:51], v[176:179], v[192:195], v[48:51]
	v_mfma_f32_16x16x32_bf16 v[80:83], v[144:147], v[200:203], v[80:83]
	v_mfma_f32_16x16x32_bf16 v[120:123], v[176:179], v[200:203], v[120:123]
	v_mfma_f32_16x16x32_bf16 v[36:39], v[144:147], v[208:211], v[36:39]
	v_mfma_f32_16x16x32_bf16 v[40:43], v[176:179], v[208:211], v[40:43]
	s_setprio 0
	s_barrier
	ds_read_b128 v[124:127], v16
	ds_read_b128 v[128:131], v16 offset:1024
	ds_read_b128 v[132:135], v16 offset:2048
	ds_read_b128 v[136:139], v16 offset:3072
	ds_read_b128 v[140:143], v17
	ds_read_b128 v[144:147], v17 offset:1024
	ds_read_b128 v[172:175], v17 offset:2048
	ds_read_b128 v[176:179], v17 offset:3072
	s_add_u32 s36, s36, 0x40180
	s_addc_u32 s37, s37, 0
	s_mov_b32 m0, s70
	v_lshl_add_u64 v[212:213], s[36:37], 0, v[6:7]
	ds_read_b128 v[180:183], v18
	ds_read_b128 v[184:187], v18 offset:1024
	ds_read_b128 v[188:191], v18 offset:2048
	ds_read_b128 v[192:195], v18 offset:3072
	ds_read_b128 v[196:199], v18 offset:4096
	ds_read_b128 v[200:203], v18 offset:5120
	ds_read_b128 v[204:207], v18 offset:6144
	ds_read_b128 v[208:211], v18 offset:7168
	global_load_lds_dwordx4 v[212:213], off
	v_lshl_add_u64 v[212:213], s[36:37], 0, v[2:3]
	s_mov_b32 m0, s64
	s_nop 0
	global_load_lds_dwordx4 v[212:213], off
	s_waitcnt vmcnt(8)
	s_waitcnt lgkmcnt(0)
	s_barrier
	s_setprio 1
	s_waitcnt lgkmcnt(0)
	v_mfma_f32_16x16x32_bf16 v[84:87], v[124:127], v[180:183], v[84:87]
	v_mfma_f32_16x16x32_bf16 v[88:91], v[132:135], v[180:183], v[88:91]
	v_mfma_f32_16x16x32_bf16 v[92:95], v[124:127], v[188:191], v[92:95]
	v_mfma_f32_16x16x32_bf16 v[96:99], v[132:135], v[188:191], v[96:99]
	v_mfma_f32_16x16x32_bf16 v[100:103], v[124:127], v[196:199], v[100:103]
	v_mfma_f32_16x16x32_bf16 v[104:107], v[132:135], v[196:199], v[104:107]
	v_mfma_f32_16x16x32_bf16 v[108:111], v[124:127], v[204:207], v[108:111]
	v_mfma_f32_16x16x32_bf16 v[112:115], v[132:135], v[204:207], v[112:115]
	v_mfma_f32_16x16x32_bf16 v[84:87], v[128:131], v[184:187], v[84:87]
	v_mfma_f32_16x16x32_bf16 v[88:91], v[136:139], v[184:187], v[88:91]
	v_mfma_f32_16x16x32_bf16 v[92:95], v[128:131], v[192:195], v[92:95]
	v_mfma_f32_16x16x32_bf16 v[96:99], v[136:139], v[192:195], v[96:99]
	v_mfma_f32_16x16x32_bf16 v[100:103], v[128:131], v[200:203], v[100:103]
	v_mfma_f32_16x16x32_bf16 v[104:107], v[136:139], v[200:203], v[104:107]
	v_mfma_f32_16x16x32_bf16 v[108:111], v[128:131], v[208:211], v[108:111]
	v_mfma_f32_16x16x32_bf16 v[112:115], v[136:139], v[208:211], v[112:115]
	s_setprio 0
	s_setprio 1
	v_mfma_f32_16x16x32_bf16 v[116:119], v[140:143], v[180:183], v[116:119]
	v_mfma_f32_16x16x32_bf16 v[52:55], v[172:175], v[180:183], v[52:55]
	v_mfma_f32_16x16x32_bf16 v[56:59], v[140:143], v[188:191], v[56:59]
	v_mfma_f32_16x16x32_bf16 v[60:63], v[172:175], v[188:191], v[60:63]
	v_mfma_f32_16x16x32_bf16 v[64:67], v[140:143], v[196:199], v[64:67]
	v_mfma_f32_16x16x32_bf16 v[68:71], v[172:175], v[196:199], v[68:71]
	v_mfma_f32_16x16x32_bf16 v[72:75], v[140:143], v[204:207], v[72:75]
	v_mfma_f32_16x16x32_bf16 v[76:79], v[172:175], v[204:207], v[76:79]
	v_mfma_f32_16x16x32_bf16 v[116:119], v[144:147], v[184:187], v[116:119]
	v_mfma_f32_16x16x32_bf16 v[52:55], v[176:179], v[184:187], v[52:55]
	v_mfma_f32_16x16x32_bf16 v[56:59], v[144:147], v[192:195], v[56:59]
	v_mfma_f32_16x16x32_bf16 v[60:63], v[176:179], v[192:195], v[60:63]
	v_mfma_f32_16x16x32_bf16 v[64:67], v[144:147], v[200:203], v[64:67]
	v_mfma_f32_16x16x32_bf16 v[68:71], v[176:179], v[200:203], v[68:71]
	v_mfma_f32_16x16x32_bf16 v[72:75], v[144:147], v[208:211], v[72:75]
	v_mfma_f32_16x16x32_bf16 v[76:79], v[176:179], v[208:211], v[76:79]
	s_setprio 0
	s_barrier
	s_mov_b32 m0, s68
	v_lshl_add_u64 v[212:213], s[2:3], 0, v[4:5]
	s_add_u32 s36, s2, 0x80000
	ds_read_b128 v[180:183], v18 offset:16384
	ds_read_b128 v[184:187], v18 offset:17408
	ds_read_b128 v[188:191], v18 offset:18432
	ds_read_b128 v[192:195], v18 offset:19456
	ds_read_b128 v[196:199], v18 offset:20480
	ds_read_b128 v[200:203], v18 offset:21504
	ds_read_b128 v[204:207], v18 offset:22528
	ds_read_b128 v[208:211], v18 offset:23552
	global_load_lds_dwordx4 v[212:213], off
	v_lshl_add_u64 v[214:215], s[2:3], 0, v[0:1]
	s_mov_b32 m0, s65
	s_addc_u32 s37, s3, 0
	global_load_lds_dwordx4 v[214:215], off
	v_lshl_add_u64 v[216:217], s[36:37], 0, v[4:5]
	s_mov_b32 m0, s66
	v_lshl_add_u64 v[218:219], s[40:41], 0, v[2:3]
	global_load_lds_dwordx4 v[216:217], off
	v_lshl_add_u64 v[216:217], s[36:37], 0, v[0:1]
	s_mov_b32 m0, s67
	s_nop 0
	global_load_lds_dwordx4 v[216:217], off
	v_lshl_add_u64 v[216:217], s[40:41], 0, v[6:7]
	s_mov_b32 m0, s45
	s_nop 0
	global_load_lds_dwordx4 v[216:217], off
	s_mov_b32 m0, s46
	s_nop 0
	global_load_lds_dwordx4 v[218:219], off
	s_waitcnt vmcnt(8)
	s_waitcnt lgkmcnt(0)
	s_barrier
	s_setprio 1
	s_waitcnt lgkmcnt(0)
	v_mfma_f32_16x16x32_bf16 v[148:151], v[124:127], v[180:183], v[148:151]
	v_mfma_f32_16x16x32_bf16 v[152:155], v[132:135], v[180:183], v[152:155]
	v_mfma_f32_16x16x32_bf16 v[156:159], v[124:127], v[188:191], v[156:159]
	v_mfma_f32_16x16x32_bf16 v[160:163], v[132:135], v[188:191], v[160:163]
	v_mfma_f32_16x16x32_bf16 v[164:167], v[124:127], v[196:199], v[164:167]
	v_mfma_f32_16x16x32_bf16 v[168:171], v[132:135], v[196:199], v[168:171]
	v_mfma_f32_16x16x32_bf16 v[20:23], v[124:127], v[204:207], v[20:23]
	v_mfma_f32_16x16x32_bf16 v[24:27], v[132:135], v[204:207], v[24:27]
	v_mfma_f32_16x16x32_bf16 v[148:151], v[128:131], v[184:187], v[148:151]
	v_mfma_f32_16x16x32_bf16 v[152:155], v[136:139], v[184:187], v[152:155]
	v_mfma_f32_16x16x32_bf16 v[156:159], v[128:131], v[192:195], v[156:159]
	v_mfma_f32_16x16x32_bf16 v[160:163], v[136:139], v[192:195], v[160:163]
	v_mfma_f32_16x16x32_bf16 v[164:167], v[128:131], v[200:203], v[164:167]
	v_mfma_f32_16x16x32_bf16 v[168:171], v[136:139], v[200:203], v[168:171]
	v_mfma_f32_16x16x32_bf16 v[20:23], v[128:131], v[208:211], v[20:23]
	v_mfma_f32_16x16x32_bf16 v[24:27], v[136:139], v[208:211], v[24:27]
	s_setprio 0
	s_setprio 1
	v_mfma_f32_16x16x32_bf16 v[28:31], v[140:143], v[180:183], v[28:31]
	v_mfma_f32_16x16x32_bf16 v[32:35], v[172:175], v[180:183], v[32:35]
	v_mfma_f32_16x16x32_bf16 v[44:47], v[140:143], v[188:191], v[44:47]
	v_mfma_f32_16x16x32_bf16 v[48:51], v[172:175], v[188:191], v[48:51]
	v_mfma_f32_16x16x32_bf16 v[80:83], v[140:143], v[196:199], v[80:83]
	v_mfma_f32_16x16x32_bf16 v[120:123], v[172:175], v[196:199], v[120:123]
	v_mfma_f32_16x16x32_bf16 v[36:39], v[140:143], v[204:207], v[36:39]
	v_mfma_f32_16x16x32_bf16 v[40:43], v[172:175], v[204:207], v[40:43]
	v_mfma_f32_16x16x32_bf16 v[28:31], v[144:147], v[184:187], v[28:31]
	v_mfma_f32_16x16x32_bf16 v[32:35], v[176:179], v[184:187], v[32:35]
	v_mfma_f32_16x16x32_bf16 v[44:47], v[144:147], v[192:195], v[44:47]
	v_mfma_f32_16x16x32_bf16 v[48:51], v[176:179], v[192:195], v[48:51]
	v_mfma_f32_16x16x32_bf16 v[80:83], v[144:147], v[200:203], v[80:83]
	v_mfma_f32_16x16x32_bf16 v[120:123], v[176:179], v[200:203], v[120:123]
	v_mfma_f32_16x16x32_bf16 v[36:39], v[144:147], v[208:211], v[36:39]
	v_mfma_f32_16x16x32_bf16 v[40:43], v[176:179], v[208:211], v[40:43]
	s_setprio 0
	s_barrier
	ds_read_b128 v[124:127], v19
	ds_read_b128 v[128:131], v19 offset:1024
	ds_read_b128 v[132:135], v19 offset:2048
	ds_read_b128 v[136:139], v19 offset:3072
	ds_read_b128 v[140:143], v222
	ds_read_b128 v[144:147], v222 offset:1024
	ds_read_b128 v[172:175], v222 offset:2048
	ds_read_b128 v[176:179], v222 offset:3072
	s_add_u32 s36, s40, 0x40000
	s_addc_u32 s37, s41, 0
	s_mov_b32 m0, s47
	v_lshl_add_u64 v[220:221], s[36:37], 0, v[6:7]
	ds_read_b128 v[180:183], v18 offset:32768
	ds_read_b128 v[184:187], v18 offset:33792
	ds_read_b128 v[188:191], v18 offset:34816
	ds_read_b128 v[192:195], v18 offset:35840
	ds_read_b128 v[196:199], v18 offset:36864
	ds_read_b128 v[200:203], v18 offset:37888
	ds_read_b128 v[204:207], v18 offset:38912
	ds_read_b128 v[208:211], v18 offset:39936
	global_load_lds_dwordx4 v[220:221], off
	v_lshl_add_u64 v[220:221], s[36:37], 0, v[2:3]
	s_mov_b32 m0, s48
	s_nop 0
	global_load_lds_dwordx4 v[220:221], off
	s_waitcnt vmcnt(8)
	s_waitcnt lgkmcnt(0)
	s_barrier
	s_setprio 1
	s_waitcnt lgkmcnt(0)
	v_mfma_f32_16x16x32_bf16 v[84:87], v[124:127], v[180:183], v[84:87]
	v_mfma_f32_16x16x32_bf16 v[88:91], v[132:135], v[180:183], v[88:91]
	v_mfma_f32_16x16x32_bf16 v[92:95], v[124:127], v[188:191], v[92:95]
	v_mfma_f32_16x16x32_bf16 v[96:99], v[132:135], v[188:191], v[96:99]
	v_mfma_f32_16x16x32_bf16 v[100:103], v[124:127], v[196:199], v[100:103]
	v_mfma_f32_16x16x32_bf16 v[104:107], v[132:135], v[196:199], v[104:107]
	v_mfma_f32_16x16x32_bf16 v[108:111], v[124:127], v[204:207], v[108:111]
	v_mfma_f32_16x16x32_bf16 v[112:115], v[132:135], v[204:207], v[112:115]
	v_mfma_f32_16x16x32_bf16 v[84:87], v[128:131], v[184:187], v[84:87]
	v_mfma_f32_16x16x32_bf16 v[88:91], v[136:139], v[184:187], v[88:91]
	v_mfma_f32_16x16x32_bf16 v[92:95], v[128:131], v[192:195], v[92:95]
	v_mfma_f32_16x16x32_bf16 v[96:99], v[136:139], v[192:195], v[96:99]
	v_mfma_f32_16x16x32_bf16 v[100:103], v[128:131], v[200:203], v[100:103]
	v_mfma_f32_16x16x32_bf16 v[104:107], v[136:139], v[200:203], v[104:107]
	v_mfma_f32_16x16x32_bf16 v[108:111], v[128:131], v[208:211], v[108:111]
	v_mfma_f32_16x16x32_bf16 v[112:115], v[136:139], v[208:211], v[112:115]
	s_setprio 0
	s_setprio 1
	v_mfma_f32_16x16x32_bf16 v[116:119], v[140:143], v[180:183], v[116:119]
	v_mfma_f32_16x16x32_bf16 v[52:55], v[172:175], v[180:183], v[52:55]
	v_mfma_f32_16x16x32_bf16 v[56:59], v[140:143], v[188:191], v[56:59]
	v_mfma_f32_16x16x32_bf16 v[60:63], v[172:175], v[188:191], v[60:63]
	v_mfma_f32_16x16x32_bf16 v[64:67], v[140:143], v[196:199], v[64:67]
	v_mfma_f32_16x16x32_bf16 v[68:71], v[172:175], v[196:199], v[68:71]
	v_mfma_f32_16x16x32_bf16 v[72:75], v[140:143], v[204:207], v[72:75]
	v_mfma_f32_16x16x32_bf16 v[76:79], v[172:175], v[204:207], v[76:79]
	v_mfma_f32_16x16x32_bf16 v[116:119], v[144:147], v[184:187], v[116:119]
	v_mfma_f32_16x16x32_bf16 v[52:55], v[176:179], v[184:187], v[52:55]
	v_mfma_f32_16x16x32_bf16 v[56:59], v[144:147], v[192:195], v[56:59]
	v_mfma_f32_16x16x32_bf16 v[60:63], v[176:179], v[192:195], v[60:63]
	v_mfma_f32_16x16x32_bf16 v[64:67], v[144:147], v[200:203], v[64:67]
	v_mfma_f32_16x16x32_bf16 v[68:71], v[176:179], v[200:203], v[68:71]
	v_mfma_f32_16x16x32_bf16 v[72:75], v[144:147], v[208:211], v[72:75]
	v_mfma_f32_16x16x32_bf16 v[76:79], v[176:179], v[208:211], v[76:79]
	s_setprio 0
	s_barrier
	s_mov_b32 m0, s71
	v_lshl_add_u64 v[212:213], v[212:213], 0, s[4:5]
	s_add_u32 s2, s2, 0x80080
	ds_read_b128 v[180:183], v18 offset:49152
	ds_read_b128 v[184:187], v18 offset:50176
	ds_read_b128 v[188:191], v18 offset:51200
	ds_read_b128 v[192:195], v18 offset:52224
	ds_read_b128 v[196:199], v18 offset:53248
	ds_read_b128 v[200:203], v18 offset:54272
	ds_read_b128 v[204:207], v18 offset:55296
	ds_read_b128 v[208:211], v18 offset:56320
	global_load_lds_dwordx4 v[212:213], off
	v_lshl_add_u64 v[212:213], v[214:215], 0, s[4:5]
	s_mov_b32 m0, s69
	s_addc_u32 s3, s3, 0
	global_load_lds_dwordx4 v[212:213], off
	v_lshl_add_u64 v[212:213], s[2:3], 0, v[4:5]
	s_mov_b32 m0, s38
	s_nop 0
	global_load_lds_dwordx4 v[212:213], off
	v_lshl_add_u64 v[212:213], s[2:3], 0, v[0:1]
	s_mov_b32 m0, s39
	s_nop 0
	global_load_lds_dwordx4 v[212:213], off
	v_lshl_add_u64 v[212:213], v[216:217], 0, s[4:5]
	s_mov_b32 m0, s52
	s_nop 0
	global_load_lds_dwordx4 v[212:213], off
	v_lshl_add_u64 v[212:213], v[218:219], 0, s[4:5]
	s_mov_b32 m0, s53
	s_nop 0
	global_load_lds_dwordx4 v[212:213], off
	s_waitcnt vmcnt(8)
	s_waitcnt lgkmcnt(0)
	s_barrier
	s_setprio 1
	s_waitcnt lgkmcnt(0)
	v_mfma_f32_16x16x32_bf16 v[148:151], v[124:127], v[180:183], v[148:151]
	v_mfma_f32_16x16x32_bf16 v[152:155], v[132:135], v[180:183], v[152:155]
	v_mfma_f32_16x16x32_bf16 v[156:159], v[124:127], v[188:191], v[156:159]
	v_mfma_f32_16x16x32_bf16 v[160:163], v[132:135], v[188:191], v[160:163]
	v_mfma_f32_16x16x32_bf16 v[164:167], v[124:127], v[196:199], v[164:167]
	v_mfma_f32_16x16x32_bf16 v[168:171], v[132:135], v[196:199], v[168:171]
	v_mfma_f32_16x16x32_bf16 v[20:23], v[124:127], v[204:207], v[20:23]
	v_mfma_f32_16x16x32_bf16 v[24:27], v[132:135], v[204:207], v[24:27]
	v_mfma_f32_16x16x32_bf16 v[148:151], v[128:131], v[184:187], v[148:151]
	v_mfma_f32_16x16x32_bf16 v[152:155], v[136:139], v[184:187], v[152:155]
	v_mfma_f32_16x16x32_bf16 v[156:159], v[128:131], v[192:195], v[156:159]
	v_mfma_f32_16x16x32_bf16 v[160:163], v[136:139], v[192:195], v[160:163]
	v_mfma_f32_16x16x32_bf16 v[164:167], v[128:131], v[200:203], v[164:167]
	v_mfma_f32_16x16x32_bf16 v[168:171], v[136:139], v[200:203], v[168:171]
	v_mfma_f32_16x16x32_bf16 v[20:23], v[128:131], v[208:211], v[20:23]
	v_mfma_f32_16x16x32_bf16 v[24:27], v[136:139], v[208:211], v[24:27]
	s_setprio 0
	s_setprio 1
	v_mfma_f32_16x16x32_bf16 v[28:31], v[140:143], v[180:183], v[28:31]
	v_mfma_f32_16x16x32_bf16 v[32:35], v[172:175], v[180:183], v[32:35]
	v_mfma_f32_16x16x32_bf16 v[44:47], v[140:143], v[188:191], v[44:47]
	v_mfma_f32_16x16x32_bf16 v[48:51], v[172:175], v[188:191], v[48:51]
	v_mfma_f32_16x16x32_bf16 v[80:83], v[140:143], v[196:199], v[80:83]
	v_mfma_f32_16x16x32_bf16 v[120:123], v[172:175], v[196:199], v[120:123]
	v_mfma_f32_16x16x32_bf16 v[36:39], v[140:143], v[204:207], v[36:39]
	v_mfma_f32_16x16x32_bf16 v[40:43], v[172:175], v[204:207], v[40:43]
	v_mfma_f32_16x16x32_bf16 v[28:31], v[144:147], v[184:187], v[28:31]
	v_mfma_f32_16x16x32_bf16 v[32:35], v[176:179], v[184:187], v[32:35]
	v_mfma_f32_16x16x32_bf16 v[44:47], v[144:147], v[192:195], v[44:47]
	v_mfma_f32_16x16x32_bf16 v[48:51], v[176:179], v[192:195], v[48:51]
	v_mfma_f32_16x16x32_bf16 v[80:83], v[144:147], v[200:203], v[80:83]
	v_mfma_f32_16x16x32_bf16 v[120:123], v[176:179], v[200:203], v[120:123]
	v_mfma_f32_16x16x32_bf16 v[36:39], v[144:147], v[208:211], v[36:39]
	v_mfma_f32_16x16x32_bf16 v[40:43], v[176:179], v[208:211], v[40:43]
	s_setprio 0
	s_barrier
	v_lshl_add_u32 v124, s7, 8, v14
	s_ashr_i32 s7, s6, 31
	s_lshl_b64 s[2:3], s[6:7], 21
	v_ashrrev_i32_e32 v125, 31, v124
	s_add_u32 s2, s49, s2
	v_lshlrev_b64 v[124:125], 10, v[124:125]
	s_addc_u32 s3, s51, s3
	v_lshl_add_u64 v[124:125], s[2:3], 0, v[124:125]
	v_lshl_add_u64 v[124:125], v[124:125], 0, v[12:13]
	s_mov_b64 s[2:3], 0x4000
	global_store_dwordx4 v[124:125], v[84:87], off
	global_store_dwordx4 v[124:125], v[88:91], off offset:64
	global_store_dwordx4 v[124:125], v[116:119], off offset:512
	global_store_dwordx4 v[124:125], v[52:55], off offset:576
	s_add_i32 s56, s56, s76
	s_mov_b32 s6, s63
	v_lshl_add_u64 v[52:53], v[124:125], 0, s[2:3]
	s_movk_i32 s2, 0x4000
	v_add_co_u32_e32 v54, vcc, s2, v124
	s_mov_b64 s[2:3], 0x8000
	s_nop 0
	v_addc_co_u32_e32 v55, vcc, 0, v125, vcc
	global_store_dwordx4 v[54:55], v[92:95], off
	global_store_dwordx4 v[52:53], v[96:99], off offset:64
	global_store_dwordx4 v[52:53], v[56:59], off offset:512
	global_store_dwordx4 v[52:53], v[60:63], off offset:576
	v_lshl_add_u64 v[52:53], v[124:125], 0, s[2:3]
	s_mov_b32 s2, 0x8000
	v_add_co_u32_e32 v54, vcc, s2, v124
	s_mov_b32 s2, 0xc000
	s_nop 0
	v_addc_co_u32_e32 v55, vcc, 0, v125, vcc
	global_store_dwordx4 v[54:55], v[100:103], off
	global_store_dwordx4 v[52:53], v[104:107], off offset:64
	global_store_dwordx4 v[52:53], v[64:67], off offset:512
	global_store_dwordx4 v[52:53], v[68:71], off offset:576
	v_add_co_u32_e32 v54, vcc, s2, v124
	v_lshl_add_u64 v[52:53], v[124:125], 0, s[12:13]
	s_nop 0
	v_addc_co_u32_e32 v55, vcc, 0, v125, vcc
	global_store_dwordx4 v[54:55], v[108:111], off
	global_store_dwordx4 v[52:53], v[112:115], off offset:64
	global_store_dwordx4 v[52:53], v[72:75], off offset:512
	global_store_dwordx4 v[52:53], v[76:79], off offset:576
	v_add_co_u32_e32 v54, vcc, s59, v124
	v_lshl_add_u64 v[52:53], v[124:125], 0, s[14:15]
	s_nop 0
	v_addc_co_u32_e32 v55, vcc, 0, v125, vcc
	global_store_dwordx4 v[54:55], v[148:151], off
	global_store_dwordx4 v[52:53], v[152:155], off offset:64
	global_store_dwordx4 v[52:53], v[28:31], off offset:512
	global_store_dwordx4 v[52:53], v[32:35], off offset:576
	s_mov_b32 s7, s62
	v_add_co_u32_e32 v30, vcc, s60, v124
	v_lshl_add_u64 v[28:29], v[124:125], 0, s[16:17]
	s_nop 0
	v_addc_co_u32_e32 v31, vcc, 0, v125, vcc
	global_store_dwordx4 v[30:31], v[156:159], off
	global_store_dwordx4 v[28:29], v[160:163], off offset:64
	global_store_dwordx4 v[28:29], v[44:47], off offset:512
	global_store_dwordx4 v[28:29], v[48:51], off offset:576
	v_add_co_u32_e32 v30, vcc, s61, v124
	v_lshl_add_u64 v[28:29], v[124:125], 0, s[18:19]
	s_nop 0
	v_addc_co_u32_e32 v31, vcc, 0, v125, vcc
	global_store_dwordx4 v[30:31], v[164:167], off
	global_store_dwordx4 v[28:29], v[168:171], off offset:64
	global_store_dwordx4 v[28:29], v[80:83], off offset:512
	global_store_dwordx4 v[28:29], v[120:123], off offset:576
	v_add_co_u32_e32 v30, vcc, 0x2c000, v124
	s_mov_b64 s[38:39], s[34:35]
	s_nop 0
	v_addc_co_u32_e32 v31, vcc, 0, v125, vcc
	s_andn2_b64 vcc, exec, s[0:1]
	s_mov_b64 s[36:37], s[30:31]
	v_lshl_add_u64 v[28:29], v[124:125], 0, s[20:21]
	global_store_dwordx4 v[30:31], v[20:23], off
	global_store_dwordx4 v[28:29], v[24:27], off offset:64
	global_store_dwordx4 v[28:29], v[36:39], off offset:512
	global_store_dwordx4 v[28:29], v[40:43], off offset:576
	s_cbranch_vccz .LBB0_368

.LBB0_412:
	s_add_i32 s0, 0, 0x23f68
	v_mov_b32_e32 v0, s7
	v_mov_b32_e32 v4, s0
	ds_read_b128 v[0:3], v0
	ds_read_b64 v[4:5], v4
	s_cmpk_gt_i32 s84, 0x7ff
	s_waitcnt lgkmcnt(1)
	v_readfirstlane_b32 s6, v0
	v_readfirstlane_b32 s7, v1
	v_readfirstlane_b32 s2, v2
	v_readfirstlane_b32 s3, v3
	s_waitcnt lgkmcnt(0)
	v_readfirstlane_b32 s4, v4
	v_readfirstlane_b32 s5, v5
	s_mov_b64 s[40:41], s[4:5]
	s_cbranch_scc1 .LBB0_417
	s_cmpk_lg_i32 s76, 0x100
	s_cbranch_scc1 .Lcfl_nodma
	v_mbcnt_lo_u32_b32 v200, -1, 0
	v_mbcnt_hi_u32_b32 v200, -1, v200
	s_lshl_b32 s0, s79, 14
	v_lshl_add_u32 v200, v200, 4, s0
	s_mov_b32 m0, s0
	s_nop 0
	global_load_lds_dwordx4 v200, s[40:41]
	global_load_lds_dwordx4 v200, s[40:41] offset:1024
	global_load_lds_dwordx4 v200, s[40:41] offset:2048
	global_load_lds_dwordx4 v200, s[40:41] offset:3072
	v_add_u32_e32 v200, 0x1000, v200
	s_add_i32 m0, s0, 0x1000
	s_nop 0
	global_load_lds_dwordx4 v200, s[40:41]
	global_load_lds_dwordx4 v200, s[40:41] offset:1024
	global_load_lds_dwordx4 v200, s[40:41] offset:2048
	global_load_lds_dwordx4 v200, s[40:41] offset:3072
	v_add_u32_e32 v200, 0x1000, v200
	s_add_i32 m0, s0, 0x2000
	s_nop 0
	global_load_lds_dwordx4 v200, s[40:41]
	global_load_lds_dwordx4 v200, s[40:41] offset:1024
	global_load_lds_dwordx4 v200, s[40:41] offset:2048
	global_load_lds_dwordx4 v200, s[40:41] offset:3072
	v_add_u32_e32 v200, 0x1000, v200
	s_add_i32 m0, s0, 0x3000
	s_nop 0
	global_load_lds_dwordx4 v200, s[40:41]
	global_load_lds_dwordx4 v200, s[40:41] offset:1024
	global_load_lds_dwordx4 v200, s[40:41] offset:2048
	global_load_lds_dwordx4 v200, s[40:41] offset:3072
.Lcfl_nodma:
	v_mbcnt_lo_u32_b32 v0, s10, 0
	v_mbcnt_hi_u32_b32 v4, s10, v0
	v_mov_b32_e32 v53, 0
	v_lshlrev_b32_e32 v0, 2, v4
	v_mov_b32_e32 v1, v53
	v_lshl_add_u64 v[56:57], s[4:5], 0, v[0:1]
	s_mov_b64 s[4:5], 0x10000
	v_lshlrev_b32_e32 v0, 1, v4
	v_lshlrev_b32_e32 v52, 4, v4
	v_lshl_add_u64 v[58:59], v[56:57], 0, s[4:5]
	v_lshl_add_u64 v[0:1], s[2:3], 0, v[0:1]
	s_mov_b64 s[4:5], 0x1d00000
	v_lshl_add_u64 v[60:61], v[0:1], 0, s[4:5]
	v_lshl_add_u64 v[0:1], s[2:3], 0, v[52:53]
	s_mov_b64 s[2:3], 0x1c40000
	v_lshl_add_u64 v[64:65], v[0:1], 0, s[2:3]
	s_mov_b64 s[2:3], 0x1c40400
	v_lshl_add_u64 v[66:67], v[0:1], 0, s[2:3]
	s_mov_b64 s[2:3], 0x1c40800
	v_lshl_add_u64 v[68:69], v[0:1], 0, s[2:3]
	s_mov_b64 s[2:3], 0x1c40c00
	v_lshl_add_u64 v[70:71], v[0:1], 0, s[2:3]
	s_mov_b64 s[2:3], 0x1c41000
	v_lshl_add_u64 v[72:73], v[0:1], 0, s[2:3]
	s_mov_b64 s[2:3], 0x1c41400
	v_lshl_add_u64 v[74:75], v[0:1], 0, s[2:3]
	s_mov_b64 s[2:3], 0x1c41800
	v_lshl_add_u64 v[76:77], v[0:1], 0, s[2:3]
	s_mov_b64 s[2:3], 0x1c41c00
	v_lshl_add_u64 v[78:79], v[0:1], 0, s[2:3]
	s_mov_b64 s[2:3], 0x1c42000
	v_lshl_add_u64 v[80:81], v[0:1], 0, s[2:3]
	s_mov_b64 s[2:3], 0x1c42400
	v_lshl_add_u64 v[82:83], v[0:1], 0, s[2:3]
	s_mov_b64 s[2:3], 0x1c42800
	v_lshl_add_u64 v[84:85], v[0:1], 0, s[2:3]
	s_mov_b64 s[2:3], 0x1c42c00
	v_lshl_add_u64 v[86:87], v[0:1], 0, s[2:3]
	s_mov_b64 s[2:3], 0x1c43000
	v_lshl_add_u64 v[88:89], v[0:1], 0, s[2:3]
	s_mov_b64 s[2:3], 0x1c43400
	v_lshl_add_u64 v[90:91], v[0:1], 0, s[2:3]
	s_mov_b64 s[2:3], 0x1c43800
	v_lshl_add_u64 v[92:93], v[0:1], 0, s[2:3]
	s_mov_b64 s[2:3], 0x1c43c00
	v_lshl_add_u64 v[94:95], v[0:1], 0, s[2:3]
	s_mov_b64 s[2:3], 0x1c44000
	v_lshl_add_u64 v[96:97], v[0:1], 0, s[2:3]
	s_mov_b64 s[2:3], 0x1c44400
	v_lshl_add_u64 v[98:99], v[0:1], 0, s[2:3]
	s_mov_b64 s[2:3], 0x1c44800
	v_lshl_add_u64 v[100:101], v[0:1], 0, s[2:3]
	s_mov_b64 s[2:3], 0x1c44c00
	v_lshl_add_u64 v[102:103], v[0:1], 0, s[2:3]
	s_mov_b64 s[2:3], 0x1c45000
	v_lshl_add_u64 v[104:105], v[0:1], 0, s[2:3]
	s_mov_b64 s[2:3], 0x1c45400
	v_lshl_add_u64 v[106:107], v[0:1], 0, s[2:3]
	s_mov_b64 s[2:3], 0x1c45800
	v_lshl_add_u64 v[108:109], v[0:1], 0, s[2:3]
	s_mov_b64 s[2:3], 0x1c45c00
	v_lshl_add_u64 v[110:111], v[0:1], 0, s[2:3]
	s_mov_b64 s[2:3], 0x1c46000
	v_lshl_add_u64 v[112:113], v[0:1], 0, s[2:3]
	s_mov_b64 s[2:3], 0x1c46400
	v_lshl_add_u64 v[114:115], v[0:1], 0, s[2:3]
	s_mov_b64 s[2:3], 0x1c46800
	v_lshl_add_u64 v[116:117], v[0:1], 0, s[2:3]
	s_mov_b64 s[2:3], 0x1c46c00
	v_lshl_add_u64 v[118:119], v[0:1], 0, s[2:3]
	s_mov_b64 s[2:3], 0x1c47000
	v_lshl_add_u64 v[120:121], v[0:1], 0, s[2:3]
	s_mov_b64 s[2:3], 0x1c47400
	s_lshl_b32 s0, s79, 11
	v_lshl_add_u64 v[122:123], v[0:1], 0, s[2:3]
	s_mov_b64 s[2:3], 0x1c47800
	s_add_i32 s8, s0, 0
	v_lshl_add_u64 v[2:3], s[6:7], 0, v[52:53]
	s_mov_b64 s[6:7], 0x2000000
	s_movk_i32 s0, 0xfe
	v_lshl_add_u64 v[124:125], v[0:1], 0, s[2:3]
	s_mov_b64 s[2:3], 0x1c47c00
	s_mov_b32 s1, 0
	v_lshl_add_u64 v[54:55], v[2:3], 0, s[6:7]
	v_add_u32_e32 v128, s8, v52
	v_mad_u64_u32 v[62:63], s[4:5], v4, s0, v[60:61]
	v_lshl_add_u64 v[126:127], v[0:1], 0, s[2:3]
	s_mov_b32 s6, 0x1000000
	s_mov_b32 s7, 0x200000
	s_mov_b32 s9, 0x1200000
	s_mov_b32 s10, 0x400000
	s_mov_b32 s11, 0x1400000
	s_mov_b32 s12, 0x600000
	s_mov_b32 s13, 0x1600000
	s_mov_b32 s14, 0x800000
	s_mov_b32 s15, 0x1800000
	s_mov_b32 s16, 0xa00000
	s_mov_b32 s17, 0x1a00000
	s_mov_b32 s18, 0xc00000
	s_mov_b32 s19, 0x1c00000
	s_mov_b32 s20, 0xe00000
	s_mov_b32 s21, 0x1e00000
	s_movk_i32 s24, 0x7fff
	s_mov_b32 s2, s84
.LBB0_414:
	global_load_dwordx4 v[130:133], v[64:65], off
	global_load_dwordx4 v[134:137], v[66:67], off
	global_load_dwordx4 v[138:141], v[68:69], off
	global_load_dwordx4 v[142:145], v[70:71], off
	global_load_dwordx4 v[146:149], v[72:73], off
	global_load_dwordx4 v[150:153], v[74:75], off
	global_load_dwordx4 v[154:157], v[76:77], off
	global_load_dwordx4 v[158:161], v[78:79], off
	global_load_dwordx4 v[0:3], v[80:81], off
	global_load_dwordx4 v[4:7], v[82:83], off
	global_load_dwordx4 v[8:11], v[84:85], off
	global_load_dwordx4 v[12:15], v[86:87], off
	global_load_dwordx4 v[16:19], v[88:89], off
	global_load_dwordx4 v[20:23], v[90:91], off
	global_load_dwordx4 v[24:27], v[92:93], off
	global_load_dwordx4 v[28:31], v[94:95], off
	global_load_dwordx4 v[32:35], v[96:97], off
	global_load_dwordx4 v[36:39], v[98:99], off
	global_load_dwordx4 v[40:43], v[100:101], off
	global_load_dwordx4 v[44:47], v[102:103], off
	global_load_dwordx4 v[48:51], v[104:105], off
	global_load_dwordx4 v[162:165], v[106:107], off
	global_load_dwordx4 v[166:169], v[108:109], off
	global_load_dwordx4 v[170:173], v[110:111], off
	global_load_dwordx4 v[174:177], v[112:113], off
	global_load_dwordx4 v[178:181], v[114:115], off
	global_load_dwordx4 v[182:185], v[116:117], off
	global_load_dwordx4 v[186:189], v[118:119], off
	global_load_dwordx4 v[190:193], v[120:121], off
	global_load_dwordx4 v[194:197], v[122:123], off
	global_load_dwordx4 v[198:201], v[124:125], off
	global_load_dwordx4 v[202:205], v[126:127], off
	s_ashr_i32 s3, s2, 31
	s_lshl_b64 s[4:5], s[2:3], 10
	v_lshl_add_u64 v[234:235], v[54:55], 0, s[4:5]
	v_add_co_u32_e32 v210, vcc, s6, v234
	s_mov_b64 s[4:5], 0
	s_nop 0
	v_addc_co_u32_e32 v211, vcc, 0, v235, vcc
	v_add_co_u32_e32 v214, vcc, s7, v234
	s_mov_b32 s0, s8
	s_nop 0
	v_addc_co_u32_e32 v215, vcc, 0, v235, vcc
	v_add_co_u32_e32 v218, vcc, s9, v234
	s_waitcnt vmcnt(31)
	v_pk_add_f32 v[130:131], v[130:131], 0 op_sel_hi:[1,0]
	v_addc_co_u32_e32 v219, vcc, 0, v235, vcc
	v_add_co_u32_e32 v222, vcc, s10, v234
	s_waitcnt vmcnt(30)
	v_pk_add_f32 v[134:135], v[134:135], 0 op_sel_hi:[1,0]
	v_addc_co_u32_e32 v223, vcc, 0, v235, vcc
	v_add_co_u32_e32 v226, vcc, s11, v234
	s_waitcnt vmcnt(28)
	v_pk_add_f32 v[134:135], v[134:135], v[142:143]
	v_addc_co_u32_e32 v227, vcc, 0, v235, vcc
	v_add_co_u32_e32 v230, vcc, s12, v234
	s_waitcnt vmcnt(26)
	v_pk_add_f32 v[134:135], v[134:135], v[150:151]
	v_addc_co_u32_e32 v231, vcc, 0, v235, vcc
	s_waitcnt vmcnt(24)
	v_pk_add_f32 v[242:243], v[134:135], v[158:159]
	v_add_co_u32_e32 v134, vcc, s13, v234
	v_pk_add_f32 v[130:131], v[130:131], v[138:139]
	s_nop 0
	v_addc_co_u32_e32 v135, vcc, 0, v235, vcc
	v_add_co_u32_e32 v138, vcc, s14, v234
	v_pk_add_f32 v[130:131], v[130:131], v[146:147]
	s_nop 0
	v_addc_co_u32_e32 v139, vcc, 0, v235, vcc
	v_add_co_u32_e32 v142, vcc, s15, v234
	v_pk_add_f32 v[132:133], v[132:133], 0 op_sel_hi:[1,0]
	s_nop 0
	v_addc_co_u32_e32 v143, vcc, 0, v235, vcc
	v_add_co_u32_e32 v146, vcc, s16, v234
	v_pk_add_f32 v[238:239], v[130:131], v[154:155]
	s_nop 0
	v_addc_co_u32_e32 v147, vcc, 0, v235, vcc
	v_add_co_u32_e32 v150, vcc, s17, v234
	v_pk_add_f32 v[136:137], v[136:137], 0 op_sel_hi:[1,0]
	s_nop 0
	v_addc_co_u32_e32 v151, vcc, 0, v235, vcc
	v_add_co_u32_e32 v154, vcc, s18, v234
	v_pk_add_f32 v[132:133], v[132:133], v[140:141]
	s_nop 0
	v_addc_co_u32_e32 v155, vcc, 0, v235, vcc
	v_pk_add_f32 v[136:137], v[136:137], v[144:145]
	v_pk_add_f32 v[132:133], v[132:133], v[148:149]
	v_add_co_u32_e32 v158, vcc, s19, v234
	global_load_dwordx4 v[206:209], v[234:235], off
	s_nop 0
	global_load_dwordx4 v[210:213], v[210:211], off
	s_nop 0
	global_load_dwordx4 v[214:217], v[214:215], off
	s_nop 0
	global_load_dwordx4 v[218:221], v[218:219], off
	s_nop 0
	global_load_dwordx4 v[222:225], v[222:223], off
	s_nop 0
	global_load_dwordx4 v[226:229], v[226:227], off
	v_pk_add_f32 v[136:137], v[136:137], v[152:153]
	v_pk_add_f32 v[132:133], v[132:133], v[156:157]
	v_addc_co_u32_e32 v159, vcc, 0, v235, vcc
	v_pk_add_f32 v[240:241], v[136:137], v[160:161]
	s_waitcnt vmcnt(29)
	v_pk_add_f32 v[2:3], v[132:133], v[2:3]
	global_load_dwordx4 v[130:133], v[230:231], off
	s_nop 0
	global_load_dwordx4 v[134:137], v[134:135], off
	v_add_co_u32_e32 v230, vcc, s20, v234
	global_load_dwordx4 v[138:141], v[138:139], off
	s_nop 0
	global_load_dwordx4 v[142:145], v[142:143], off
	v_addc_co_u32_e32 v231, vcc, 0, v235, vcc
	global_load_dwordx4 v[146:149], v[146:147], off
	s_nop 0
	global_load_dwordx4 v[150:153], v[150:151], off
	v_add_co_u32_e32 v234, vcc, s21, v234
	global_load_dwordx4 v[154:157], v[154:155], off
	s_nop 0
	global_load_dwordx4 v[158:161], v[158:159], off
	v_addc_co_u32_e32 v235, vcc, 0, v235, vcc
	global_load_dwordx4 v[230:233], v[230:231], off
	v_pk_add_f32 v[0:1], v[238:239], v[0:1]
	global_load_dwordx4 v[234:237], v[234:235], off
	s_waitcnt vmcnt(38)
	v_pk_add_f32 v[6:7], v[240:241], v[6:7]
	v_pk_add_f32 v[4:5], v[242:243], v[4:5]
	s_waitcnt vmcnt(37)
	v_pk_add_f32 v[2:3], v[2:3], v[10:11]
	v_pk_add_f32 v[0:1], v[0:1], v[8:9]
	s_waitcnt vmcnt(36)
	v_pk_add_f32 v[6:7], v[6:7], v[14:15]
	v_pk_add_f32 v[4:5], v[4:5], v[12:13]
	s_waitcnt vmcnt(35)
	v_pk_add_f32 v[2:3], v[2:3], v[18:19]
	v_pk_add_f32 v[0:1], v[0:1], v[16:17]
	s_waitcnt vmcnt(34)
	v_pk_add_f32 v[6:7], v[6:7], v[22:23]
	v_pk_add_f32 v[4:5], v[4:5], v[20:21]
	s_waitcnt vmcnt(33)
	v_pk_add_f32 v[2:3], v[2:3], v[26:27]
	v_pk_add_f32 v[0:1], v[0:1], v[24:25]
	s_waitcnt vmcnt(32)
	v_pk_add_f32 v[6:7], v[6:7], v[30:31]
	v_pk_add_f32 v[4:5], v[4:5], v[28:29]
	s_waitcnt vmcnt(31)
	v_pk_add_f32 v[2:3], v[2:3], v[34:35]
	v_pk_add_f32 v[0:1], v[0:1], v[32:33]
	s_waitcnt vmcnt(30)
	v_pk_add_f32 v[6:7], v[6:7], v[38:39]
	v_pk_add_f32 v[4:5], v[4:5], v[36:37]
	s_waitcnt vmcnt(29)
	v_pk_add_f32 v[2:3], v[2:3], v[42:43]
	v_pk_add_f32 v[0:1], v[0:1], v[40:41]
	s_waitcnt vmcnt(28)
	v_pk_add_f32 v[6:7], v[6:7], v[46:47]
	v_pk_add_f32 v[4:5], v[4:5], v[44:45]
	s_waitcnt vmcnt(27)
	v_pk_add_f32 v[2:3], v[2:3], v[50:51]
	v_pk_add_f32 v[0:1], v[0:1], v[48:49]
	s_waitcnt vmcnt(26)
	v_pk_add_f32 v[6:7], v[6:7], v[164:165]
	v_pk_add_f32 v[4:5], v[4:5], v[162:163]
	s_waitcnt vmcnt(25)
	v_pk_add_f32 v[2:3], v[2:3], v[168:169]
	v_pk_add_f32 v[0:1], v[0:1], v[166:167]
	s_waitcnt vmcnt(24)
	v_pk_add_f32 v[6:7], v[6:7], v[172:173]
	v_pk_add_f32 v[4:5], v[4:5], v[170:171]
	s_waitcnt vmcnt(23)
	v_pk_add_f32 v[2:3], v[2:3], v[176:177]
	v_pk_add_f32 v[0:1], v[0:1], v[174:175]
	s_waitcnt vmcnt(22)
	v_pk_add_f32 v[6:7], v[6:7], v[180:181]
	v_pk_add_f32 v[4:5], v[4:5], v[178:179]
	s_waitcnt vmcnt(21)
	v_pk_add_f32 v[2:3], v[2:3], v[184:185]
	v_pk_add_f32 v[0:1], v[0:1], v[182:183]
	s_waitcnt vmcnt(20)
	v_pk_add_f32 v[6:7], v[6:7], v[188:189]
	v_pk_add_f32 v[4:5], v[4:5], v[186:187]
	s_waitcnt vmcnt(19)
	v_pk_add_f32 v[2:3], v[2:3], v[192:193]
	v_pk_add_f32 v[0:1], v[0:1], v[190:191]
	s_waitcnt vmcnt(18)
	v_pk_add_f32 v[6:7], v[6:7], v[196:197]
	v_pk_add_f32 v[4:5], v[4:5], v[194:195]
	s_waitcnt vmcnt(17)
	v_pk_add_f32 v[2:3], v[2:3], v[200:201]
	v_pk_add_f32 v[0:1], v[0:1], v[198:199]
	s_waitcnt vmcnt(16)
	v_pk_add_f32 v[6:7], v[6:7], v[204:205]
	v_pk_add_f32 v[4:5], v[4:5], v[202:203]
	s_waitcnt vmcnt(15)
	v_pk_add_f32 v[2:3], v[2:3], v[208:209]
	v_pk_add_f32 v[0:1], v[0:1], v[206:207]
	s_waitcnt vmcnt(14)
	v_pk_add_f32 v[6:7], v[6:7], v[212:213]
	v_pk_add_f32 v[4:5], v[4:5], v[210:211]
	s_waitcnt vmcnt(13)
	v_pk_add_f32 v[2:3], v[2:3], v[216:217]
	v_pk_add_f32 v[0:1], v[0:1], v[214:215]
	s_waitcnt vmcnt(12)
	v_pk_add_f32 v[6:7], v[6:7], v[220:221]
	v_pk_add_f32 v[4:5], v[4:5], v[218:219]
	s_waitcnt vmcnt(11)
	v_pk_add_f32 v[2:3], v[2:3], v[224:225]
	v_pk_add_f32 v[0:1], v[0:1], v[222:223]
	s_waitcnt vmcnt(10)
	v_pk_add_f32 v[6:7], v[6:7], v[228:229]
	v_pk_add_f32 v[4:5], v[4:5], v[226:227]
	s_waitcnt vmcnt(9)
	v_pk_add_f32 v[2:3], v[2:3], v[132:133]
	v_pk_add_f32 v[0:1], v[0:1], v[130:131]
	s_waitcnt vmcnt(8)
	v_pk_add_f32 v[6:7], v[6:7], v[136:137]
	v_pk_add_f32 v[4:5], v[4:5], v[134:135]
	s_waitcnt vmcnt(7)
	v_pk_add_f32 v[2:3], v[2:3], v[140:141]
	v_pk_add_f32 v[0:1], v[0:1], v[138:139]
	s_waitcnt vmcnt(6)
	v_pk_add_f32 v[6:7], v[6:7], v[144:145]
	v_pk_add_f32 v[4:5], v[4:5], v[142:143]
	s_waitcnt vmcnt(5)
	v_pk_add_f32 v[2:3], v[2:3], v[148:149]
	v_pk_add_f32 v[0:1], v[0:1], v[146:147]
	s_waitcnt vmcnt(4)
	v_pk_add_f32 v[6:7], v[6:7], v[152:153]
	v_pk_add_f32 v[4:5], v[4:5], v[150:151]
	s_waitcnt vmcnt(3)
	v_pk_add_f32 v[2:3], v[2:3], v[156:157]
	v_pk_add_f32 v[0:1], v[0:1], v[154:155]
	s_waitcnt vmcnt(2)
	v_pk_add_f32 v[6:7], v[6:7], v[160:161]
	v_pk_add_f32 v[4:5], v[4:5], v[158:159]
	s_waitcnt vmcnt(1)
	v_pk_add_f32 v[0:1], v[0:1], v[230:231]
	v_pk_add_f32 v[2:3], v[2:3], v[232:233]
	v_mul_f32_e32 v8, 0xbfb8aa3b, v0
	s_waitcnt vmcnt(0)
	v_pk_add_f32 v[6:7], v[6:7], v[236:237]
	v_pk_add_f32 v[4:5], v[4:5], v[234:235]
	v_mul_f32_e32 v9, 0xbfb8aa3b, v1
	v_mul_f32_e32 v10, 0xbfb8aa3b, v2
	v_mul_f32_e32 v11, 0xbfb8aa3b, v3
	v_exp_f32_e32 v8, v8
	v_exp_f32_e32 v9, v9
	v_exp_f32_e32 v10, v10
	v_exp_f32_e32 v11, v11
	v_mul_f32_e32 v12, 0xbfb8aa3b, v4
	v_mul_f32_e32 v13, 0xbfb8aa3b, v5
	v_mul_f32_e32 v14, 0xbfb8aa3b, v6
	v_mul_f32_e32 v15, 0xbfb8aa3b, v7
	v_exp_f32_e32 v12, v12
	v_exp_f32_e32 v13, v13
	v_exp_f32_e32 v14, v14
	v_exp_f32_e32 v15, v15
	v_add_f32_e32 v8, 1.0, v8
	v_add_f32_e32 v9, 1.0, v9
	v_add_f32_e32 v10, 1.0, v10
	v_add_f32_e32 v11, 1.0, v11
	v_rcp_f32_e32 v8, v8
	v_rcp_f32_e32 v9, v9
	v_rcp_f32_e32 v10, v10
	v_rcp_f32_e32 v11, v11
	v_add_f32_e32 v12, 1.0, v12
	v_add_f32_e32 v13, 1.0, v13
	v_add_f32_e32 v14, 1.0, v14
	v_add_f32_e32 v15, 1.0, v15
	v_rcp_f32_e32 v12, v12
	v_rcp_f32_e32 v14, v14
	v_rcp_f32_e32 v15, v15
	v_rcp_f32_e32 v13, v13
	v_pk_mul_f32 v[2:3], v[2:3], v[10:11]
	v_pk_mul_f32 v[0:1], v[0:1], v[8:9]
	v_pk_mul_f32 v[6:7], v[6:7], v[14:15]
	v_pk_mul_f32 v[4:5], v[4:5], v[12:13]
	s_cmpk_lg_i32 s76, 0x100
	s_cbranch_scc1 .Lcfl_generic
	v_mbcnt_lo_u32_b32 v8, -1, 0
	v_mbcnt_hi_u32_b32 v8, -1, v8
	s_lshl_b32 s0, s79, 11
	s_add_i32 s0, s0, 0x24000
	v_lshl_add_u32 v9, v8, 2, s0
	ds_write_b32 v9, v0
	ds_write_b32 v9, v1 offset:256
	ds_write_b32 v9, v2 offset:512
	ds_write_b32 v9, v3 offset:768
	ds_write_b32 v9, v4 offset:1024
	ds_write_b32 v9, v5 offset:1280
	ds_write_b32 v9, v6 offset:1536
	ds_write_b32 v9, v7 offset:1792
	s_waitcnt vmcnt(0) lgkmcnt(0)
	s_barrier
	v_lshrrev_b32_e32 v10, 4, v8
	v_lshl_add_u32 v10, v10, 8, s0
	v_lshlrev_b32_e32 v11, 4, v8
	v_add_u32_e32 v12, 0x10000, v11
	v_mov_b32_e32 v16, 0
	v_mov_b32_e32 v17, 0
	v_mov_b32_e32 v18, 0
	v_mov_b32_e32 v19, 0
	v_mov_b32_e32 v20, 0
	v_mov_b32_e32 v21, 0
	v_mov_b32_e32 v22, 0
	v_mov_b32_e32 v23, 0
	ds_read_b128 v[24:27], v10 offset:0
	ds_read_b128 v[28:31], v10 offset:1024
	ds_read_b128 v[132:135], v11 offset:0
	ds_read_b128 v[136:139], v11 offset:1024
	ds_read_b128 v[140:143], v12 offset:0
	ds_read_b128 v[144:147], v12 offset:1024
	ds_read_b128 v[148:151], v11 offset:2048
	ds_read_b128 v[152:155], v11 offset:3072
	ds_read_b128 v[156:159], v12 offset:2048
	ds_read_b128 v[160:163], v12 offset:3072
	s_waitcnt lgkmcnt(4)
	v_fmac_f32_e32 v16, v24, v132
	v_fmac_f32_e32 v17, v24, v133
	v_fmac_f32_e32 v18, v24, v134
	v_fmac_f32_e32 v19, v24, v135
	v_fmac_f32_e32 v16, v25, v136
	v_fmac_f32_e32 v17, v25, v137
	v_fmac_f32_e32 v18, v25, v138
	v_fmac_f32_e32 v19, v25, v139
	v_fmac_f32_e32 v20, v28, v140
	v_fmac_f32_e32 v21, v28, v141
	v_fmac_f32_e32 v22, v28, v142
	v_fmac_f32_e32 v23, v28, v143
	v_fmac_f32_e32 v20, v29, v144
	v_fmac_f32_e32 v21, v29, v145
	v_fmac_f32_e32 v22, v29, v146
	v_fmac_f32_e32 v23, v29, v147
	ds_read_b128 v[32:35], v10 offset:16
	ds_read_b128 v[36:39], v10 offset:1040
	ds_read_b128 v[132:135], v11 offset:4096
	ds_read_b128 v[136:139], v11 offset:5120
	ds_read_b128 v[140:143], v12 offset:4096
	ds_read_b128 v[144:147], v12 offset:5120
	s_waitcnt lgkmcnt(6)
	v_fmac_f32_e32 v16, v26, v148
	v_fmac_f32_e32 v17, v26, v149
	v_fmac_f32_e32 v18, v26, v150
	v_fmac_f32_e32 v19, v26, v151
	v_fmac_f32_e32 v16, v27, v152
	v_fmac_f32_e32 v17, v27, v153
	v_fmac_f32_e32 v18, v27, v154
	v_fmac_f32_e32 v19, v27, v155
	v_fmac_f32_e32 v20, v30, v156
	v_fmac_f32_e32 v21, v30, v157
	v_fmac_f32_e32 v22, v30, v158
	v_fmac_f32_e32 v23, v30, v159
	v_fmac_f32_e32 v20, v31, v160
	v_fmac_f32_e32 v21, v31, v161
	v_fmac_f32_e32 v22, v31, v162
	v_fmac_f32_e32 v23, v31, v163
	ds_read_b128 v[148:151], v11 offset:6144
	ds_read_b128 v[152:155], v11 offset:7168
	ds_read_b128 v[156:159], v12 offset:6144
	ds_read_b128 v[160:163], v12 offset:7168
	s_waitcnt lgkmcnt(4)
	v_fmac_f32_e32 v16, v32, v132
	v_fmac_f32_e32 v17, v32, v133
	v_fmac_f32_e32 v18, v32, v134
	v_fmac_f32_e32 v19, v32, v135
	v_fmac_f32_e32 v16, v33, v136
	v_fmac_f32_e32 v17, v33, v137
	v_fmac_f32_e32 v18, v33, v138
	v_fmac_f32_e32 v19, v33, v139
	v_fmac_f32_e32 v20, v36, v140
	v_fmac_f32_e32 v21, v36, v141
	v_fmac_f32_e32 v22, v36, v142
	v_fmac_f32_e32 v23, v36, v143
	v_fmac_f32_e32 v20, v37, v144
	v_fmac_f32_e32 v21, v37, v145
	v_fmac_f32_e32 v22, v37, v146
	v_fmac_f32_e32 v23, v37, v147
	ds_read_b128 v[24:27], v10 offset:32
	ds_read_b128 v[28:31], v10 offset:1056
	ds_read_b128 v[132:135], v11 offset:8192
	ds_read_b128 v[136:139], v11 offset:9216
	ds_read_b128 v[140:143], v12 offset:8192
	ds_read_b128 v[144:147], v12 offset:9216
	s_waitcnt lgkmcnt(6)
	v_fmac_f32_e32 v16, v34, v148
	v_fmac_f32_e32 v17, v34, v149
	v_fmac_f32_e32 v18, v34, v150
	v_fmac_f32_e32 v19, v34, v151
	v_fmac_f32_e32 v16, v35, v152
	v_fmac_f32_e32 v17, v35, v153
	v_fmac_f32_e32 v18, v35, v154
	v_fmac_f32_e32 v19, v35, v155
	v_fmac_f32_e32 v20, v38, v156
	v_fmac_f32_e32 v21, v38, v157
	v_fmac_f32_e32 v22, v38, v158
	v_fmac_f32_e32 v23, v38, v159
	v_fmac_f32_e32 v20, v39, v160
	v_fmac_f32_e32 v21, v39, v161
	v_fmac_f32_e32 v22, v39, v162
	v_fmac_f32_e32 v23, v39, v163
	ds_read_b128 v[148:151], v11 offset:10240
	ds_read_b128 v[152:155], v11 offset:11264
	ds_read_b128 v[156:159], v12 offset:10240
	ds_read_b128 v[160:163], v12 offset:11264
	s_waitcnt lgkmcnt(4)
	v_fmac_f32_e32 v16, v24, v132
	v_fmac_f32_e32 v17, v24, v133
	v_fmac_f32_e32 v18, v24, v134
	v_fmac_f32_e32 v19, v24, v135
	v_fmac_f32_e32 v16, v25, v136
	v_fmac_f32_e32 v17, v25, v137
	v_fmac_f32_e32 v18, v25, v138
	v_fmac_f32_e32 v19, v25, v139
	v_fmac_f32_e32 v20, v28, v140
	v_fmac_f32_e32 v21, v28, v141
	v_fmac_f32_e32 v22, v28, v142
	v_fmac_f32_e32 v23, v28, v143
	v_fmac_f32_e32 v20, v29, v144
	v_fmac_f32_e32 v21, v29, v145
	v_fmac_f32_e32 v22, v29, v146
	v_fmac_f32_e32 v23, v29, v147
	ds_read_b128 v[32:35], v10 offset:48
	ds_read_b128 v[36:39], v10 offset:1072
	ds_read_b128 v[132:135], v11 offset:12288
	ds_read_b128 v[136:139], v11 offset:13312
	ds_read_b128 v[140:143], v12 offset:12288
	ds_read_b128 v[144:147], v12 offset:13312
	s_waitcnt lgkmcnt(6)
	v_fmac_f32_e32 v16, v26, v148
	v_fmac_f32_e32 v17, v26, v149
	v_fmac_f32_e32 v18, v26, v150
	v_fmac_f32_e32 v19, v26, v151
	v_fmac_f32_e32 v16, v27, v152
	v_fmac_f32_e32 v17, v27, v153
	v_fmac_f32_e32 v18, v27, v154
	v_fmac_f32_e32 v19, v27, v155
	v_fmac_f32_e32 v20, v30, v156
	v_fmac_f32_e32 v21, v30, v157
	v_fmac_f32_e32 v22, v30, v158
	v_fmac_f32_e32 v23, v30, v159
	v_fmac_f32_e32 v20, v31, v160
	v_fmac_f32_e32 v21, v31, v161
	v_fmac_f32_e32 v22, v31, v162
	v_fmac_f32_e32 v23, v31, v163
	ds_read_b128 v[148:151], v11 offset:14336
	ds_read_b128 v[152:155], v11 offset:15360
	ds_read_b128 v[156:159], v12 offset:14336
	ds_read_b128 v[160:163], v12 offset:15360
	s_waitcnt lgkmcnt(4)
	v_fmac_f32_e32 v16, v32, v132
	v_fmac_f32_e32 v17, v32, v133
	v_fmac_f32_e32 v18, v32, v134
	v_fmac_f32_e32 v19, v32, v135
	v_fmac_f32_e32 v16, v33, v136
	v_fmac_f32_e32 v17, v33, v137
	v_fmac_f32_e32 v18, v33, v138
	v_fmac_f32_e32 v19, v33, v139
	v_fmac_f32_e32 v20, v36, v140
	v_fmac_f32_e32 v21, v36, v141
	v_fmac_f32_e32 v22, v36, v142
	v_fmac_f32_e32 v23, v36, v143
	v_fmac_f32_e32 v20, v37, v144
	v_fmac_f32_e32 v21, v37, v145
	v_fmac_f32_e32 v22, v37, v146
	v_fmac_f32_e32 v23, v37, v147
	ds_read_b128 v[24:27], v10 offset:64
	ds_read_b128 v[28:31], v10 offset:1088
	ds_read_b128 v[132:135], v11 offset:16384
	ds_read_b128 v[136:139], v11 offset:17408
	ds_read_b128 v[140:143], v12 offset:16384
	ds_read_b128 v[144:147], v12 offset:17408
	s_waitcnt lgkmcnt(6)
	v_fmac_f32_e32 v16, v34, v148
	v_fmac_f32_e32 v17, v34, v149
	v_fmac_f32_e32 v18, v34, v150
	v_fmac_f32_e32 v19, v34, v151
	v_fmac_f32_e32 v16, v35, v152
	v_fmac_f32_e32 v17, v35, v153
	v_fmac_f32_e32 v18, v35, v154
	v_fmac_f32_e32 v19, v35, v155
	v_fmac_f32_e32 v20, v38, v156
	v_fmac_f32_e32 v21, v38, v157
	v_fmac_f32_e32 v22, v38, v158
	v_fmac_f32_e32 v23, v38, v159
	v_fmac_f32_e32 v20, v39, v160
	v_fmac_f32_e32 v21, v39, v161
	v_fmac_f32_e32 v22, v39, v162
	v_fmac_f32_e32 v23, v39, v163
	ds_read_b128 v[148:151], v11 offset:18432
	ds_read_b128 v[152:155], v11 offset:19456
	ds_read_b128 v[156:159], v12 offset:18432
	ds_read_b128 v[160:163], v12 offset:19456
	s_waitcnt lgkmcnt(4)
	v_fmac_f32_e32 v16, v24, v132
	v_fmac_f32_e32 v17, v24, v133
	v_fmac_f32_e32 v18, v24, v134
	v_fmac_f32_e32 v19, v24, v135
	v_fmac_f32_e32 v16, v25, v136
	v_fmac_f32_e32 v17, v25, v137
	v_fmac_f32_e32 v18, v25, v138
	v_fmac_f32_e32 v19, v25, v139
	v_fmac_f32_e32 v20, v28, v140
	v_fmac_f32_e32 v21, v28, v141
	v_fmac_f32_e32 v22, v28, v142
	v_fmac_f32_e32 v23, v28, v143
	v_fmac_f32_e32 v20, v29, v144
	v_fmac_f32_e32 v21, v29, v145
	v_fmac_f32_e32 v22, v29, v146
	v_fmac_f32_e32 v23, v29, v147
	ds_read_b128 v[32:35], v10 offset:80
	ds_read_b128 v[36:39], v10 offset:1104
	ds_read_b128 v[132:135], v11 offset:20480
	ds_read_b128 v[136:139], v11 offset:21504
	ds_read_b128 v[140:143], v12 offset:20480
	ds_read_b128 v[144:147], v12 offset:21504
	s_waitcnt lgkmcnt(6)
	v_fmac_f32_e32 v16, v26, v148
	v_fmac_f32_e32 v17, v26, v149
	v_fmac_f32_e32 v18, v26, v150
	v_fmac_f32_e32 v19, v26, v151
	v_fmac_f32_e32 v16, v27, v152
	v_fmac_f32_e32 v17, v27, v153
	v_fmac_f32_e32 v18, v27, v154
	v_fmac_f32_e32 v19, v27, v155
	v_fmac_f32_e32 v20, v30, v156
	v_fmac_f32_e32 v21, v30, v157
	v_fmac_f32_e32 v22, v30, v158
	v_fmac_f32_e32 v23, v30, v159
	v_fmac_f32_e32 v20, v31, v160
	v_fmac_f32_e32 v21, v31, v161
	v_fmac_f32_e32 v22, v31, v162
	v_fmac_f32_e32 v23, v31, v163
	ds_read_b128 v[148:151], v11 offset:22528
	ds_read_b128 v[152:155], v11 offset:23552
	ds_read_b128 v[156:159], v12 offset:22528
	ds_read_b128 v[160:163], v12 offset:23552
	s_waitcnt lgkmcnt(4)
	v_fmac_f32_e32 v16, v32, v132
	v_fmac_f32_e32 v17, v32, v133
	v_fmac_f32_e32 v18, v32, v134
	v_fmac_f32_e32 v19, v32, v135
	v_fmac_f32_e32 v16, v33, v136
	v_fmac_f32_e32 v17, v33, v137
	v_fmac_f32_e32 v18, v33, v138
	v_fmac_f32_e32 v19, v33, v139
	v_fmac_f32_e32 v20, v36, v140
	v_fmac_f32_e32 v21, v36, v141
	v_fmac_f32_e32 v22, v36, v142
	v_fmac_f32_e32 v23, v36, v143
	v_fmac_f32_e32 v20, v37, v144
	v_fmac_f32_e32 v21, v37, v145
	v_fmac_f32_e32 v22, v37, v146
	v_fmac_f32_e32 v23, v37, v147
	ds_read_b128 v[24:27], v10 offset:96
	ds_read_b128 v[28:31], v10 offset:1120
	ds_read_b128 v[132:135], v11 offset:24576
	ds_read_b128 v[136:139], v11 offset:25600
	ds_read_b128 v[140:143], v12 offset:24576
	ds_read_b128 v[144:147], v12 offset:25600
	s_waitcnt lgkmcnt(6)
	v_fmac_f32_e32 v16, v34, v148
	v_fmac_f32_e32 v17, v34, v149
	v_fmac_f32_e32 v18, v34, v150
	v_fmac_f32_e32 v19, v34, v151
	v_fmac_f32_e32 v16, v35, v152
	v_fmac_f32_e32 v17, v35, v153
	v_fmac_f32_e32 v18, v35, v154
	v_fmac_f32_e32 v19, v35, v155
	v_fmac_f32_e32 v20, v38, v156
	v_fmac_f32_e32 v21, v38, v157
	v_fmac_f32_e32 v22, v38, v158
	v_fmac_f32_e32 v23, v38, v159
	v_fmac_f32_e32 v20, v39, v160
	v_fmac_f32_e32 v21, v39, v161
	v_fmac_f32_e32 v22, v39, v162
	v_fmac_f32_e32 v23, v39, v163
	ds_read_b128 v[148:151], v11 offset:26624
	ds_read_b128 v[152:155], v11 offset:27648
	ds_read_b128 v[156:159], v12 offset:26624
	ds_read_b128 v[160:163], v12 offset:27648
	s_waitcnt lgkmcnt(4)
	v_fmac_f32_e32 v16, v24, v132
	v_fmac_f32_e32 v17, v24, v133
	v_fmac_f32_e32 v18, v24, v134
	v_fmac_f32_e32 v19, v24, v135
	v_fmac_f32_e32 v16, v25, v136
	v_fmac_f32_e32 v17, v25, v137
	v_fmac_f32_e32 v18, v25, v138
	v_fmac_f32_e32 v19, v25, v139
	v_fmac_f32_e32 v20, v28, v140
	v_fmac_f32_e32 v21, v28, v141
	v_fmac_f32_e32 v22, v28, v142
	v_fmac_f32_e32 v23, v28, v143
	v_fmac_f32_e32 v20, v29, v144
	v_fmac_f32_e32 v21, v29, v145
	v_fmac_f32_e32 v22, v29, v146
	v_fmac_f32_e32 v23, v29, v147
	ds_read_b128 v[32:35], v10 offset:112
	ds_read_b128 v[36:39], v10 offset:1136
	ds_read_b128 v[132:135], v11 offset:28672
	ds_read_b128 v[136:139], v11 offset:29696
	ds_read_b128 v[140:143], v12 offset:28672
	ds_read_b128 v[144:147], v12 offset:29696
	s_waitcnt lgkmcnt(6)
	v_fmac_f32_e32 v16, v26, v148
	v_fmac_f32_e32 v17, v26, v149
	v_fmac_f32_e32 v18, v26, v150
	v_fmac_f32_e32 v19, v26, v151
	v_fmac_f32_e32 v16, v27, v152
	v_fmac_f32_e32 v17, v27, v153
	v_fmac_f32_e32 v18, v27, v154
	v_fmac_f32_e32 v19, v27, v155
	v_fmac_f32_e32 v20, v30, v156
	v_fmac_f32_e32 v21, v30, v157
	v_fmac_f32_e32 v22, v30, v158
	v_fmac_f32_e32 v23, v30, v159
	v_fmac_f32_e32 v20, v31, v160
	v_fmac_f32_e32 v21, v31, v161
	v_fmac_f32_e32 v22, v31, v162
	v_fmac_f32_e32 v23, v31, v163
	ds_read_b128 v[148:151], v11 offset:30720
	ds_read_b128 v[152:155], v11 offset:31744
	ds_read_b128 v[156:159], v12 offset:30720
	ds_read_b128 v[160:163], v12 offset:31744
	s_waitcnt lgkmcnt(4)
	v_fmac_f32_e32 v16, v32, v132
	v_fmac_f32_e32 v17, v32, v133
	v_fmac_f32_e32 v18, v32, v134
	v_fmac_f32_e32 v19, v32, v135
	v_fmac_f32_e32 v16, v33, v136
	v_fmac_f32_e32 v17, v33, v137
	v_fmac_f32_e32 v18, v33, v138
	v_fmac_f32_e32 v19, v33, v139
	v_fmac_f32_e32 v20, v36, v140
	v_fmac_f32_e32 v21, v36, v141
	v_fmac_f32_e32 v22, v36, v142
	v_fmac_f32_e32 v23, v36, v143
	v_fmac_f32_e32 v20, v37, v144
	v_fmac_f32_e32 v21, v37, v145
	v_fmac_f32_e32 v22, v37, v146
	v_fmac_f32_e32 v23, v37, v147
	ds_read_b128 v[24:27], v10 offset:128
	ds_read_b128 v[28:31], v10 offset:1152
	ds_read_b128 v[132:135], v11 offset:32768
	ds_read_b128 v[136:139], v11 offset:33792
	ds_read_b128 v[140:143], v12 offset:32768
	ds_read_b128 v[144:147], v12 offset:33792
	s_waitcnt lgkmcnt(6)
	v_fmac_f32_e32 v16, v34, v148
	v_fmac_f32_e32 v17, v34, v149
	v_fmac_f32_e32 v18, v34, v150
	v_fmac_f32_e32 v19, v34, v151
	v_fmac_f32_e32 v16, v35, v152
	v_fmac_f32_e32 v17, v35, v153
	v_fmac_f32_e32 v18, v35, v154
	v_fmac_f32_e32 v19, v35, v155
	v_fmac_f32_e32 v20, v38, v156
	v_fmac_f32_e32 v21, v38, v157
	v_fmac_f32_e32 v22, v38, v158
	v_fmac_f32_e32 v23, v38, v159
	v_fmac_f32_e32 v20, v39, v160
	v_fmac_f32_e32 v21, v39, v161
	v_fmac_f32_e32 v22, v39, v162
	v_fmac_f32_e32 v23, v39, v163
	ds_read_b128 v[148:151], v11 offset:34816
	ds_read_b128 v[152:155], v11 offset:35840
	ds_read_b128 v[156:159], v12 offset:34816
	ds_read_b128 v[160:163], v12 offset:35840
	s_waitcnt lgkmcnt(4)
	v_fmac_f32_e32 v16, v24, v132
	v_fmac_f32_e32 v17, v24, v133
	v_fmac_f32_e32 v18, v24, v134
	v_fmac_f32_e32 v19, v24, v135
	v_fmac_f32_e32 v16, v25, v136
	v_fmac_f32_e32 v17, v25, v137
	v_fmac_f32_e32 v18, v25, v138
	v_fmac_f32_e32 v19, v25, v139
	v_fmac_f32_e32 v20, v28, v140
	v_fmac_f32_e32 v21, v28, v141
	v_fmac_f32_e32 v22, v28, v142
	v_fmac_f32_e32 v23, v28, v143
	v_fmac_f32_e32 v20, v29, v144
	v_fmac_f32_e32 v21, v29, v145
	v_fmac_f32_e32 v22, v29, v146
	v_fmac_f32_e32 v23, v29, v147
	ds_read_b128 v[32:35], v10 offset:144
	ds_read_b128 v[36:39], v10 offset:1168
	ds_read_b128 v[132:135], v11 offset:36864
	ds_read_b128 v[136:139], v11 offset:37888
	ds_read_b128 v[140:143], v12 offset:36864
	ds_read_b128 v[144:147], v12 offset:37888
	s_waitcnt lgkmcnt(6)
	v_fmac_f32_e32 v16, v26, v148
	v_fmac_f32_e32 v17, v26, v149
	v_fmac_f32_e32 v18, v26, v150
	v_fmac_f32_e32 v19, v26, v151
	v_fmac_f32_e32 v16, v27, v152
	v_fmac_f32_e32 v17, v27, v153
	v_fmac_f32_e32 v18, v27, v154
	v_fmac_f32_e32 v19, v27, v155
	v_fmac_f32_e32 v20, v30, v156
	v_fmac_f32_e32 v21, v30, v157
	v_fmac_f32_e32 v22, v30, v158
	v_fmac_f32_e32 v23, v30, v159
	v_fmac_f32_e32 v20, v31, v160
	v_fmac_f32_e32 v21, v31, v161
	v_fmac_f32_e32 v22, v31, v162
	v_fmac_f32_e32 v23, v31, v163
	ds_read_b128 v[148:151], v11 offset:38912
	ds_read_b128 v[152:155], v11 offset:39936
	ds_read_b128 v[156:159], v12 offset:38912
	ds_read_b128 v[160:163], v12 offset:39936
	s_waitcnt lgkmcnt(4)
	v_fmac_f32_e32 v16, v32, v132
	v_fmac_f32_e32 v17, v32, v133
	v_fmac_f32_e32 v18, v32, v134
	v_fmac_f32_e32 v19, v32, v135
	v_fmac_f32_e32 v16, v33, v136
	v_fmac_f32_e32 v17, v33, v137
	v_fmac_f32_e32 v18, v33, v138
	v_fmac_f32_e32 v19, v33, v139
	v_fmac_f32_e32 v20, v36, v140
	v_fmac_f32_e32 v21, v36, v141
	v_fmac_f32_e32 v22, v36, v142
	v_fmac_f32_e32 v23, v36, v143
	v_fmac_f32_e32 v20, v37, v144
	v_fmac_f32_e32 v21, v37, v145
	v_fmac_f32_e32 v22, v37, v146
	v_fmac_f32_e32 v23, v37, v147
	ds_read_b128 v[24:27], v10 offset:160
	ds_read_b128 v[28:31], v10 offset:1184
	ds_read_b128 v[132:135], v11 offset:40960
	ds_read_b128 v[136:139], v11 offset:41984
	ds_read_b128 v[140:143], v12 offset:40960
	ds_read_b128 v[144:147], v12 offset:41984
	s_waitcnt lgkmcnt(6)
	v_fmac_f32_e32 v16, v34, v148
	v_fmac_f32_e32 v17, v34, v149
	v_fmac_f32_e32 v18, v34, v150
	v_fmac_f32_e32 v19, v34, v151
	v_fmac_f32_e32 v16, v35, v152
	v_fmac_f32_e32 v17, v35, v153
	v_fmac_f32_e32 v18, v35, v154
	v_fmac_f32_e32 v19, v35, v155
	v_fmac_f32_e32 v20, v38, v156
	v_fmac_f32_e32 v21, v38, v157
	v_fmac_f32_e32 v22, v38, v158
	v_fmac_f32_e32 v23, v38, v159
	v_fmac_f32_e32 v20, v39, v160
	v_fmac_f32_e32 v21, v39, v161
	v_fmac_f32_e32 v22, v39, v162
	v_fmac_f32_e32 v23, v39, v163
	ds_read_b128 v[148:151], v11 offset:43008
	ds_read_b128 v[152:155], v11 offset:44032
	ds_read_b128 v[156:159], v12 offset:43008
	ds_read_b128 v[160:163], v12 offset:44032
	s_waitcnt lgkmcnt(4)
	v_fmac_f32_e32 v16, v24, v132
	v_fmac_f32_e32 v17, v24, v133
	v_fmac_f32_e32 v18, v24, v134
	v_fmac_f32_e32 v19, v24, v135
	v_fmac_f32_e32 v16, v25, v136
	v_fmac_f32_e32 v17, v25, v137
	v_fmac_f32_e32 v18, v25, v138
	v_fmac_f32_e32 v19, v25, v139
	v_fmac_f32_e32 v20, v28, v140
	v_fmac_f32_e32 v21, v28, v141
	v_fmac_f32_e32 v22, v28, v142
	v_fmac_f32_e32 v23, v28, v143
	v_fmac_f32_e32 v20, v29, v144
	v_fmac_f32_e32 v21, v29, v145
	v_fmac_f32_e32 v22, v29, v146
	v_fmac_f32_e32 v23, v29, v147
	ds_read_b128 v[32:35], v10 offset:176
	ds_read_b128 v[36:39], v10 offset:1200
	ds_read_b128 v[132:135], v11 offset:45056
	ds_read_b128 v[136:139], v11 offset:46080
	ds_read_b128 v[140:143], v12 offset:45056
	ds_read_b128 v[144:147], v12 offset:46080
	s_waitcnt lgkmcnt(6)
	v_fmac_f32_e32 v16, v26, v148
	v_fmac_f32_e32 v17, v26, v149
	v_fmac_f32_e32 v18, v26, v150
	v_fmac_f32_e32 v19, v26, v151
	v_fmac_f32_e32 v16, v27, v152
	v_fmac_f32_e32 v17, v27, v153
	v_fmac_f32_e32 v18, v27, v154
	v_fmac_f32_e32 v19, v27, v155
	v_fmac_f32_e32 v20, v30, v156
	v_fmac_f32_e32 v21, v30, v157
	v_fmac_f32_e32 v22, v30, v158
	v_fmac_f32_e32 v23, v30, v159
	v_fmac_f32_e32 v20, v31, v160
	v_fmac_f32_e32 v21, v31, v161
	v_fmac_f32_e32 v22, v31, v162
	v_fmac_f32_e32 v23, v31, v163
	ds_read_b128 v[148:151], v11 offset:47104
	ds_read_b128 v[152:155], v11 offset:48128
	ds_read_b128 v[156:159], v12 offset:47104
	ds_read_b128 v[160:163], v12 offset:48128
	s_waitcnt lgkmcnt(4)
	v_fmac_f32_e32 v16, v32, v132
	v_fmac_f32_e32 v17, v32, v133
	v_fmac_f32_e32 v18, v32, v134
	v_fmac_f32_e32 v19, v32, v135
	v_fmac_f32_e32 v16, v33, v136
	v_fmac_f32_e32 v17, v33, v137
	v_fmac_f32_e32 v18, v33, v138
	v_fmac_f32_e32 v19, v33, v139
	v_fmac_f32_e32 v20, v36, v140
	v_fmac_f32_e32 v21, v36, v141
	v_fmac_f32_e32 v22, v36, v142
	v_fmac_f32_e32 v23, v36, v143
	v_fmac_f32_e32 v20, v37, v144
	v_fmac_f32_e32 v21, v37, v145
	v_fmac_f32_e32 v22, v37, v146
	v_fmac_f32_e32 v23, v37, v147
	ds_read_b128 v[24:27], v10 offset:192
	ds_read_b128 v[28:31], v10 offset:1216
	ds_read_b128 v[132:135], v11 offset:49152
	ds_read_b128 v[136:139], v11 offset:50176
	ds_read_b128 v[140:143], v12 offset:49152
	ds_read_b128 v[144:147], v12 offset:50176
	s_waitcnt lgkmcnt(6)
	v_fmac_f32_e32 v16, v34, v148
	v_fmac_f32_e32 v17, v34, v149
	v_fmac_f32_e32 v18, v34, v150
	v_fmac_f32_e32 v19, v34, v151
	v_fmac_f32_e32 v16, v35, v152
	v_fmac_f32_e32 v17, v35, v153
	v_fmac_f32_e32 v18, v35, v154
	v_fmac_f32_e32 v19, v35, v155
	v_fmac_f32_e32 v20, v38, v156
	v_fmac_f32_e32 v21, v38, v157
	v_fmac_f32_e32 v22, v38, v158
	v_fmac_f32_e32 v23, v38, v159
	v_fmac_f32_e32 v20, v39, v160
	v_fmac_f32_e32 v21, v39, v161
	v_fmac_f32_e32 v22, v39, v162
	v_fmac_f32_e32 v23, v39, v163
	ds_read_b128 v[148:151], v11 offset:51200
	ds_read_b128 v[152:155], v11 offset:52224
	ds_read_b128 v[156:159], v12 offset:51200
	ds_read_b128 v[160:163], v12 offset:52224
	s_waitcnt lgkmcnt(4)
	v_fmac_f32_e32 v16, v24, v132
	v_fmac_f32_e32 v17, v24, v133
	v_fmac_f32_e32 v18, v24, v134
	v_fmac_f32_e32 v19, v24, v135
	v_fmac_f32_e32 v16, v25, v136
	v_fmac_f32_e32 v17, v25, v137
	v_fmac_f32_e32 v18, v25, v138
	v_fmac_f32_e32 v19, v25, v139
	v_fmac_f32_e32 v20, v28, v140
	v_fmac_f32_e32 v21, v28, v141
	v_fmac_f32_e32 v22, v28, v142
	v_fmac_f32_e32 v23, v28, v143
	v_fmac_f32_e32 v20, v29, v144
	v_fmac_f32_e32 v21, v29, v145
	v_fmac_f32_e32 v22, v29, v146
	v_fmac_f32_e32 v23, v29, v147
	ds_read_b128 v[32:35], v10 offset:208
	ds_read_b128 v[36:39], v10 offset:1232
	ds_read_b128 v[132:135], v11 offset:53248
	ds_read_b128 v[136:139], v11 offset:54272
	ds_read_b128 v[140:143], v12 offset:53248
	ds_read_b128 v[144:147], v12 offset:54272
	s_waitcnt lgkmcnt(6)
	v_fmac_f32_e32 v16, v26, v148
	v_fmac_f32_e32 v17, v26, v149
	v_fmac_f32_e32 v18, v26, v150
	v_fmac_f32_e32 v19, v26, v151
	v_fmac_f32_e32 v16, v27, v152
	v_fmac_f32_e32 v17, v27, v153
	v_fmac_f32_e32 v18, v27, v154
	v_fmac_f32_e32 v19, v27, v155
	v_fmac_f32_e32 v20, v30, v156
	v_fmac_f32_e32 v21, v30, v157
	v_fmac_f32_e32 v22, v30, v158
	v_fmac_f32_e32 v23, v30, v159
	v_fmac_f32_e32 v20, v31, v160
	v_fmac_f32_e32 v21, v31, v161
	v_fmac_f32_e32 v22, v31, v162
	v_fmac_f32_e32 v23, v31, v163
	ds_read_b128 v[148:151], v11 offset:55296
	ds_read_b128 v[152:155], v11 offset:56320
	ds_read_b128 v[156:159], v12 offset:55296
	ds_read_b128 v[160:163], v12 offset:56320
	s_waitcnt lgkmcnt(4)
	v_fmac_f32_e32 v16, v32, v132
	v_fmac_f32_e32 v17, v32, v133
	v_fmac_f32_e32 v18, v32, v134
	v_fmac_f32_e32 v19, v32, v135
	v_fmac_f32_e32 v16, v33, v136
	v_fmac_f32_e32 v17, v33, v137
	v_fmac_f32_e32 v18, v33, v138
	v_fmac_f32_e32 v19, v33, v139
	v_fmac_f32_e32 v20, v36, v140
	v_fmac_f32_e32 v21, v36, v141
	v_fmac_f32_e32 v22, v36, v142
	v_fmac_f32_e32 v23, v36, v143
	v_fmac_f32_e32 v20, v37, v144
	v_fmac_f32_e32 v21, v37, v145
	v_fmac_f32_e32 v22, v37, v146
	v_fmac_f32_e32 v23, v37, v147
	ds_read_b128 v[24:27], v10 offset:224
	ds_read_b128 v[28:31], v10 offset:1248
	ds_read_b128 v[132:135], v11 offset:57344
	ds_read_b128 v[136:139], v11 offset:58368
	ds_read_b128 v[140:143], v12 offset:57344
	ds_read_b128 v[144:147], v12 offset:58368
	s_waitcnt lgkmcnt(6)
	v_fmac_f32_e32 v16, v34, v148
	v_fmac_f32_e32 v17, v34, v149
	v_fmac_f32_e32 v18, v34, v150
	v_fmac_f32_e32 v19, v34, v151
	v_fmac_f32_e32 v16, v35, v152
	v_fmac_f32_e32 v17, v35, v153
	v_fmac_f32_e32 v18, v35, v154
	v_fmac_f32_e32 v19, v35, v155
	v_fmac_f32_e32 v20, v38, v156
	v_fmac_f32_e32 v21, v38, v157
	v_fmac_f32_e32 v22, v38, v158
	v_fmac_f32_e32 v23, v38, v159
	v_fmac_f32_e32 v20, v39, v160
	v_fmac_f32_e32 v21, v39, v161
	v_fmac_f32_e32 v22, v39, v162
	v_fmac_f32_e32 v23, v39, v163
	ds_read_b128 v[148:151], v11 offset:59392
	ds_read_b128 v[152:155], v11 offset:60416
	ds_read_b128 v[156:159], v12 offset:59392
	ds_read_b128 v[160:163], v12 offset:60416
	s_waitcnt lgkmcnt(4)
	v_fmac_f32_e32 v16, v24, v132
	v_fmac_f32_e32 v17, v24, v133
	v_fmac_f32_e32 v18, v24, v134
	v_fmac_f32_e32 v19, v24, v135
	v_fmac_f32_e32 v16, v25, v136
	v_fmac_f32_e32 v17, v25, v137
	v_fmac_f32_e32 v18, v25, v138
	v_fmac_f32_e32 v19, v25, v139
	v_fmac_f32_e32 v20, v28, v140
	v_fmac_f32_e32 v21, v28, v141
	v_fmac_f32_e32 v22, v28, v142
	v_fmac_f32_e32 v23, v28, v143
	v_fmac_f32_e32 v20, v29, v144
	v_fmac_f32_e32 v21, v29, v145
	v_fmac_f32_e32 v22, v29, v146
	v_fmac_f32_e32 v23, v29, v147
	ds_read_b128 v[32:35], v10 offset:240
	ds_read_b128 v[36:39], v10 offset:1264
	ds_read_b128 v[132:135], v11 offset:61440
	ds_read_b128 v[136:139], v11 offset:62464
	ds_read_b128 v[140:143], v12 offset:61440
	ds_read_b128 v[144:147], v12 offset:62464
	s_waitcnt lgkmcnt(6)
	v_fmac_f32_e32 v16, v26, v148
	v_fmac_f32_e32 v17, v26, v149
	v_fmac_f32_e32 v18, v26, v150
	v_fmac_f32_e32 v19, v26, v151
	v_fmac_f32_e32 v16, v27, v152
	v_fmac_f32_e32 v17, v27, v153
	v_fmac_f32_e32 v18, v27, v154
	v_fmac_f32_e32 v19, v27, v155
	v_fmac_f32_e32 v20, v30, v156
	v_fmac_f32_e32 v21, v30, v157
	v_fmac_f32_e32 v22, v30, v158
	v_fmac_f32_e32 v23, v30, v159
	v_fmac_f32_e32 v20, v31, v160
	v_fmac_f32_e32 v21, v31, v161
	v_fmac_f32_e32 v22, v31, v162
	v_fmac_f32_e32 v23, v31, v163
	ds_read_b128 v[148:151], v11 offset:63488
	ds_read_b128 v[152:155], v11 offset:64512
	ds_read_b128 v[156:159], v12 offset:63488
	ds_read_b128 v[160:163], v12 offset:64512
	s_waitcnt lgkmcnt(4)
	v_fmac_f32_e32 v16, v32, v132
	v_fmac_f32_e32 v17, v32, v133
	v_fmac_f32_e32 v18, v32, v134
	v_fmac_f32_e32 v19, v32, v135
	v_fmac_f32_e32 v16, v33, v136
	v_fmac_f32_e32 v17, v33, v137
	v_fmac_f32_e32 v18, v33, v138
	v_fmac_f32_e32 v19, v33, v139
	v_fmac_f32_e32 v20, v36, v140
	v_fmac_f32_e32 v21, v36, v141
	v_fmac_f32_e32 v22, v36, v142
	v_fmac_f32_e32 v23, v36, v143
	v_fmac_f32_e32 v20, v37, v144
	v_fmac_f32_e32 v21, v37, v145
	v_fmac_f32_e32 v22, v37, v146
	v_fmac_f32_e32 v23, v37, v147
	s_waitcnt lgkmcnt(0)
	v_fmac_f32_e32 v16, v34, v148
	v_fmac_f32_e32 v17, v34, v149
	v_fmac_f32_e32 v18, v34, v150
	v_fmac_f32_e32 v19, v34, v151
	v_fmac_f32_e32 v16, v35, v152
	v_fmac_f32_e32 v17, v35, v153
	v_fmac_f32_e32 v18, v35, v154
	v_fmac_f32_e32 v19, v35, v155
	v_fmac_f32_e32 v20, v38, v156
	v_fmac_f32_e32 v21, v38, v157
	v_fmac_f32_e32 v22, v38, v158
	v_fmac_f32_e32 v23, v38, v159
	v_fmac_f32_e32 v20, v39, v160
	v_fmac_f32_e32 v21, v39, v161
	v_fmac_f32_e32 v22, v39, v162
	v_fmac_f32_e32 v23, v39, v163
	v_xor_b32_e32 v13, 32, v8
	v_lshlrev_b32_e32 v13, 2, v13
	ds_swizzle_b32 v72, v16 offset:0x401f
	ds_swizzle_b32 v73, v17 offset:0x401f
	ds_swizzle_b32 v74, v18 offset:0x401f
	ds_swizzle_b32 v75, v19 offset:0x401f
	ds_swizzle_b32 v76, v20 offset:0x401f
	ds_swizzle_b32 v77, v21 offset:0x401f
	ds_swizzle_b32 v78, v22 offset:0x401f
	ds_swizzle_b32 v79, v23 offset:0x401f
	s_waitcnt lgkmcnt(0)
	v_add_f32_e32 v16, v16, v72
	v_add_f32_e32 v17, v17, v73
	v_add_f32_e32 v18, v18, v74
	v_add_f32_e32 v19, v19, v75
	v_add_f32_e32 v20, v20, v76
	v_add_f32_e32 v21, v21, v77
	v_add_f32_e32 v22, v22, v78
	v_add_f32_e32 v23, v23, v79
	ds_bpermute_b32 v72, v13, v16
	ds_bpermute_b32 v73, v13, v17
	ds_bpermute_b32 v74, v13, v18
	ds_bpermute_b32 v75, v13, v19
	ds_bpermute_b32 v76, v13, v20
	ds_bpermute_b32 v77, v13, v21
	ds_bpermute_b32 v78, v13, v22
	ds_bpermute_b32 v79, v13, v23
	s_waitcnt lgkmcnt(0)
	v_add_f32_e32 v16, v16, v72
	v_add_f32_e32 v17, v17, v73
	v_add_f32_e32 v18, v18, v74
	v_add_f32_e32 v19, v19, v75
	v_add_f32_e32 v20, v20, v76
	v_add_f32_e32 v21, v21, v77
	v_add_f32_e32 v22, v22, v78
	v_add_f32_e32 v23, v23, v79
	s_and_b32 s0, s2, 0x7f
	s_cmpk_eq_i32 s0, 0x7f
	s_cselect_b64 s[4:5], -1, 0
	v_cndmask_b32_e64 v16, v16, 0, s[4:5]
	v_cndmask_b32_e64 v17, v17, 0, s[4:5]
	v_cndmask_b32_e64 v18, v18, 0, s[4:5]
	v_cndmask_b32_e64 v19, v19, 0, s[4:5]
	v_cndmask_b32_e64 v20, v20, 0, s[4:5]
	v_cndmask_b32_e64 v21, v21, 0, s[4:5]
	v_cndmask_b32_e64 v22, v22, 0, s[4:5]
	v_cndmask_b32_e64 v23, v23, 0, s[4:5]
	v_cvt_pk_bf16_f32 v80, v16, v17
	v_cvt_pk_bf16_f32 v81, v18, v19
	v_cvt_pk_bf16_f32 v82, v20, v21
	v_cvt_pk_bf16_f32 v83, v22, v23
	v_cmp_gt_u32_e32 vcc, 16, v8
	s_and_saveexec_b64 s[6:7], vcc
	v_mov_b32_e32 v85, 0
	v_mul_u32_u24_e32 v84, 6, v8
	v_lshl_add_u64 v[86:87], v[60:61], 0, v[84:85]
	s_ashr_i32 s3, s2, 31
	s_lshl_b64 s[26:27], s[2:3], 7
	v_lshl_add_u64 v[86:87], v[86:87], 0, s[26:27]
	global_store_dwordx2 v[86:87], v[80:81], off
	v_mul_u32_u24_e32 v84, 0x3fe, v8
	v_lshl_add_u64 v[88:89], v[60:61], 0, v[84:85]
	s_ashr_i32 s4, s2, 7
	s_ashr_i32 s5, s4, 31
	s_lshl_b64 s[4:5], s[4:5], 14
	s_lshl_b32 s0, s0, 1
	s_add_u32 s4, s4, s0
	s_addc_u32 s5, s5, 0
	s_add_u32 s4, s4, 0x40000
	s_addc_u32 s5, s5, 0
	v_lshl_add_u64 v[88:89], v[88:89], 0, s[4:5]
	global_store_short v[88:89], v82, off
	global_store_short_d16_hi v[88:89], v82, off offset:256
	global_store_short v[88:89], v83, off offset:512
	global_store_short_d16_hi v[88:89], v83, off offset:768
	s_mov_b64 exec, s[6:7]
	s_branch .LBB0_417
	s_nop 0
	s_nop 0
	s_nop 0
	s_nop 0
	s_nop 0
.Lcfl_generic:
	ds_write_b128 v128, v[0:3]
	ds_write_b128 v128, v[4:7] offset:1024
	s_waitcnt lgkmcnt(0)
	v_mov_b32_e32 v2, 0
	v_mov_b32_e32 v3, v53
	v_mov_b32_e32 v0, 0
	v_mov_b32_e32 v1, v53
	v_mov_b32_e32 v6, 0
	v_mov_b32_e32 v7, v53
	v_mov_b32_e32 v4, 0
	v_mov_b32_e32 v5, v53
	v_lshl_add_u64 v[186:187], v[56:57], 0, s[4:5]
	v_lshl_add_u64 v[188:189], v[58:59], 0, s[4:5]
	global_load_dword v40, v[186:187], off
	global_load_dword v41, v[186:187], off offset:256
	global_load_dword v42, v[186:187], off offset:512
	global_load_dword v43, v[186:187], off offset:768
	global_load_dword v44, v[186:187], off offset:1024
	global_load_dword v45, v[186:187], off offset:1280
	global_load_dword v46, v[186:187], off offset:1536
	global_load_dword v47, v[186:187], off offset:1792
	global_load_dword v48, v[188:189], off
	global_load_dword v49, v[188:189], off offset:256
	global_load_dword v50, v[188:189], off offset:512
	global_load_dword v51, v[188:189], off offset:768
	global_load_dword v130, v[188:189], off offset:1024
	global_load_dword v131, v[188:189], off offset:1280
	global_load_dword v132, v[188:189], off offset:1536
	global_load_dword v133, v[188:189], off offset:1792
	global_load_dword v134, v[186:187], off offset:2048
	global_load_dword v135, v[186:187], off offset:2304
	global_load_dword v136, v[186:187], off offset:2560
	global_load_dword v137, v[186:187], off offset:2816
	global_load_dword v138, v[186:187], off offset:3072
	global_load_dword v139, v[186:187], off offset:3328
	global_load_dword v140, v[186:187], off offset:3584
	global_load_dword v141, v[186:187], off offset:3840
	global_load_dword v142, v[188:189], off offset:2048
	global_load_dword v143, v[188:189], off offset:2304
	global_load_dword v144, v[188:189], off offset:2560
	global_load_dword v145, v[188:189], off offset:2816
	global_load_dword v146, v[188:189], off offset:3072
	global_load_dword v148, v[188:189], off offset:3584
	global_load_dword v149, v[188:189], off offset:3840
	global_load_dword v147, v[188:189], off offset:3328

.LBB0_498:
	v_add_u32_e32 v3, s85, v130
	v_and_b32_e32 v0, 0x3fffffe0, v3
	v_lshl_add_u32 v4, v0, 2, v2
	ds_read2st64_b32 v[0:1], v4 offset0:144 offset1:176
	s_mov_b64 s[78:79], 0
	s_waitcnt lgkmcnt(0)
	v_add_f32_e32 v5, v0, v1
	ds_read2st64_b32 v[0:1], v4 offset0:208 offset1:240
	s_waitcnt lgkmcnt(0)
	v_add_f32_e32 v0, v5, v0
	v_add_f32_e32 v0, v0, v1
	v_cndmask_b32_e64 v0, v0, v122, s[0:1]
	v_cndmask_b32_e32 v0, 0, v0, vcc
	v_bfe_u32 v20, v161, 0, 1
	v_bfe_u32 v21, v161, 1, 1
	v_bfe_u32 v22, v161, 2, 1
	v_bfe_u32 v23, v161, 3, 1
	v_bfe_u32 v24, v161, 4, 1
	v_mov_b32_e32 v1, 0
	ds_swizzle_b32 v8, v0 offset:0x041f
	ds_swizzle_b32 v9, v0 offset:0x081f
	ds_swizzle_b32 v10, v0 offset:0x0c1f
	ds_swizzle_b32 v11, v0 offset:0x101f
	ds_swizzle_b32 v12, v0 offset:0x141f
	ds_swizzle_b32 v13, v0 offset:0x181f
	ds_swizzle_b32 v14, v0 offset:0x1c1f
	ds_swizzle_b32 v15, v0 offset:0x201f
	ds_swizzle_b32 v16, v0 offset:0x241f
	ds_swizzle_b32 v17, v0 offset:0x281f
	ds_swizzle_b32 v18, v0 offset:0x2c1f
	ds_swizzle_b32 v19, v0 offset:0x301f
	s_waitcnt lgkmcnt(0)
	v_add_u32_e32 v8, v8, v20
	v_add_u32_e32 v9, v9, v21
	v_add_u32_e32 v10, v10, v21
	v_add_u32_e32 v11, v11, v22
	v_add_u32_e32 v12, v12, v22
	v_add_u32_e32 v13, v13, v22
	v_add_u32_e32 v14, v14, v22
	v_add_u32_e32 v15, v15, v23
	v_add_u32_e32 v16, v16, v23
	v_add_u32_e32 v17, v17, v23
	v_add_u32_e32 v18, v18, v23
	v_add_u32_e32 v19, v19, v23
	v_cmp_gt_u32_e64 s[72:73], v8, v0
	v_cmp_gt_u32_e64 s[74:75], v9, v0
	s_nop 0
	v_addc_co_u32_e64 v1, s[72:73], v1, 0, s[72:73]
	v_addc_co_u32_e64 v1, s[74:75], v1, 0, s[74:75]
	v_cmp_gt_u32_e64 s[72:73], v10, v0
	v_cmp_gt_u32_e64 s[74:75], v11, v0
	s_nop 0
	v_addc_co_u32_e64 v1, s[72:73], v1, 0, s[72:73]
	v_addc_co_u32_e64 v1, s[74:75], v1, 0, s[74:75]
	v_cmp_gt_u32_e64 s[72:73], v12, v0
	v_cmp_gt_u32_e64 s[74:75], v13, v0
	s_nop 0
	v_addc_co_u32_e64 v1, s[72:73], v1, 0, s[72:73]
	v_addc_co_u32_e64 v1, s[74:75], v1, 0, s[74:75]
	v_cmp_gt_u32_e64 s[72:73], v14, v0
	v_cmp_gt_u32_e64 s[74:75], v15, v0
	s_nop 0
	v_addc_co_u32_e64 v1, s[72:73], v1, 0, s[72:73]
	v_addc_co_u32_e64 v1, s[74:75], v1, 0, s[74:75]
	v_cmp_gt_u32_e64 s[72:73], v16, v0
	v_cmp_gt_u32_e64 s[74:75], v17, v0
	s_nop 0
	v_addc_co_u32_e64 v1, s[72:73], v1, 0, s[72:73]
	v_addc_co_u32_e64 v1, s[74:75], v1, 0, s[74:75]
	v_cmp_gt_u32_e64 s[72:73], v18, v0
	v_cmp_gt_u32_e64 s[74:75], v19, v0
	s_nop 0
	v_addc_co_u32_e64 v1, s[72:73], v1, 0, s[72:73]
	v_addc_co_u32_e64 v1, s[74:75], v1, 0, s[74:75]
	ds_swizzle_b32 v8, v0 offset:0x341f
	ds_swizzle_b32 v9, v0 offset:0x381f
	ds_swizzle_b32 v10, v0 offset:0x3c1f
	ds_swizzle_b32 v11, v0 offset:0x401f
	ds_swizzle_b32 v12, v0 offset:0x441f
	ds_swizzle_b32 v13, v0 offset:0x481f
	ds_swizzle_b32 v14, v0 offset:0x4c1f
	ds_swizzle_b32 v15, v0 offset:0x501f
	ds_swizzle_b32 v16, v0 offset:0x541f
	ds_swizzle_b32 v17, v0 offset:0x581f
	ds_swizzle_b32 v18, v0 offset:0x5c1f
	ds_swizzle_b32 v19, v0 offset:0x601f
	s_waitcnt lgkmcnt(0)
	v_add_u32_e32 v8, v8, v23
	v_add_u32_e32 v9, v9, v23
	v_add_u32_e32 v10, v10, v23
	v_add_u32_e32 v11, v11, v24
	v_add_u32_e32 v12, v12, v24
	v_add_u32_e32 v13, v13, v24
	v_add_u32_e32 v14, v14, v24
	v_add_u32_e32 v15, v15, v24
	v_add_u32_e32 v16, v16, v24
	v_add_u32_e32 v17, v17, v24
	v_add_u32_e32 v18, v18, v24
	v_add_u32_e32 v19, v19, v24
	v_cmp_gt_u32_e64 s[72:73], v8, v0
	v_cmp_gt_u32_e64 s[74:75], v9, v0
	s_nop 0
	v_addc_co_u32_e64 v1, s[72:73], v1, 0, s[72:73]
	v_addc_co_u32_e64 v1, s[74:75], v1, 0, s[74:75]
	v_cmp_gt_u32_e64 s[72:73], v10, v0
	v_cmp_gt_u32_e64 s[74:75], v11, v0
	s_nop 0
	v_addc_co_u32_e64 v1, s[72:73], v1, 0, s[72:73]
	v_addc_co_u32_e64 v1, s[74:75], v1, 0, s[74:75]
	v_cmp_gt_u32_e64 s[72:73], v12, v0
	v_cmp_gt_u32_e64 s[74:75], v13, v0
	s_nop 0
	v_addc_co_u32_e64 v1, s[72:73], v1, 0, s[72:73]
	v_addc_co_u32_e64 v1, s[74:75], v1, 0, s[74:75]
	v_cmp_gt_u32_e64 s[72:73], v14, v0
	v_cmp_gt_u32_e64 s[74:75], v15, v0
	s_nop 0
	v_addc_co_u32_e64 v1, s[72:73], v1, 0, s[72:73]
	v_addc_co_u32_e64 v1, s[74:75], v1, 0, s[74:75]
	v_cmp_gt_u32_e64 s[72:73], v16, v0
	v_cmp_gt_u32_e64 s[74:75], v17, v0
	s_nop 0
	v_addc_co_u32_e64 v1, s[72:73], v1, 0, s[72:73]
	v_addc_co_u32_e64 v1, s[74:75], v1, 0, s[74:75]
	v_cmp_gt_u32_e64 s[72:73], v18, v0
	v_cmp_gt_u32_e64 s[74:75], v19, v0
	s_nop 0
	v_addc_co_u32_e64 v1, s[72:73], v1, 0, s[72:73]
	v_addc_co_u32_e64 v1, s[74:75], v1, 0, s[74:75]
	ds_swizzle_b32 v8, v0 offset:0x641f
	ds_swizzle_b32 v9, v0 offset:0x681f
	ds_swizzle_b32 v10, v0 offset:0x6c1f
	ds_swizzle_b32 v11, v0 offset:0x701f
	ds_swizzle_b32 v12, v0 offset:0x741f
	ds_swizzle_b32 v13, v0 offset:0x781f
	ds_swizzle_b32 v14, v0 offset:0x7c1f
	s_waitcnt lgkmcnt(0)
	v_add_u32_e32 v8, v8, v24
	v_add_u32_e32 v9, v9, v24
	v_add_u32_e32 v10, v10, v24
	v_add_u32_e32 v11, v11, v24
	v_add_u32_e32 v12, v12, v24
	v_add_u32_e32 v13, v13, v24
	v_add_u32_e32 v14, v14, v24
	v_cmp_gt_u32_e64 s[72:73], v8, v0
	v_cmp_gt_u32_e64 s[74:75], v9, v0
	s_nop 0
	v_addc_co_u32_e64 v1, s[72:73], v1, 0, s[72:73]
	v_addc_co_u32_e64 v1, s[74:75], v1, 0, s[74:75]
	v_cmp_gt_u32_e64 s[72:73], v10, v0
	v_cmp_gt_u32_e64 s[74:75], v11, v0
	s_nop 0
	v_addc_co_u32_e64 v1, s[72:73], v1, 0, s[72:73]
	v_addc_co_u32_e64 v1, s[74:75], v1, 0, s[74:75]
	v_cmp_gt_u32_e64 s[72:73], v12, v0
	v_cmp_gt_u32_e64 s[74:75], v13, v0
	s_nop 0
	v_addc_co_u32_e64 v1, s[72:73], v1, 0, s[72:73]
	v_addc_co_u32_e64 v1, s[74:75], v1, 0, s[74:75]
	v_cmp_gt_u32_e64 s[72:73], v14, v0
	s_nop 1
	v_addc_co_u32_e64 v1, s[72:73], v1, 0, s[72:73]
	v_mov_b32_e32 v0, v1
	v_cmp_gt_u32_e64 s[72:73], 16, v0
	s_and_b64 s[72:73], s[72:73], vcc
	s_nop 0
	v_cndmask_b32_e64 v0, 0, 1, s[72:73]
	v_cmp_ne_u32_e64 s[74:75], 0, v0
	v_cmp_lt_i32_e64 s[72:73], 31, v59
	s_and_saveexec_b64 s[80:81], s[72:73]
	s_xor_b64 s[80:81], exec, s[80:81]
	s_cbranch_execnz .LBB0_501
	s_or_saveexec_b64 s[80:81], s[80:81]
	v_mov_b64_e32 v[0:1], s[76:77]
	s_xor_b64 exec, exec, s[80:81]
	s_cbranch_execnz .LBB0_504

.LBB0_515:
	s_waitcnt lgkmcnt(3)
	v_mfma_f32_32x32x16_bf16 v[48:63], v[100:103], v[64:67], 0
	s_waitcnt lgkmcnt(2)
	v_mfma_f32_32x32x16_bf16 v[48:63], v[96:99], v[68:71], v[48:63]
	s_waitcnt lgkmcnt(1)
	v_mfma_f32_32x32x16_bf16 v[48:63], v[92:95], v[72:75], v[48:63]
	s_waitcnt lgkmcnt(0)
	v_mfma_f32_32x32x16_bf16 v[48:63], v[88:91], v[76:79], v[48:63]
	s_nop 2
	ds_read_b128 v[32:35], v131 offset:4608
	ds_read_b128 v[88:91], v131 offset:4640
	s_waitcnt lgkmcnt(1)
	v_mfma_f32_32x32x16_bf16 v[32:47], v[32:35], v[64:67], 0
	s_waitcnt lgkmcnt(0)
	v_mfma_f32_32x32x16_bf16 v[32:47], v[88:91], v[68:71], v[32:47]
	ds_read_b128 v[88:91], v131 offset:4672
	s_waitcnt lgkmcnt(0)
	v_mfma_f32_32x32x16_bf16 v[32:47], v[88:91], v[72:75], v[32:47]
	ds_read_b128 v[88:91], v131 offset:4704
	s_waitcnt lgkmcnt(0)
	v_mfma_f32_32x32x16_bf16 v[32:47], v[88:91], v[76:79], v[32:47]
	s_and_b64 vcc, s[66:67], s[0:1]
	v_cndmask_b32_e32 v48, v120, v48, vcc
	s_and_b64 vcc, s[66:67], s[10:11]
	v_cndmask_b32_e32 v49, v120, v49, vcc
	s_and_b64 vcc, s[66:67], s[2:3]
	v_cndmask_b32_e32 v50, v120, v50, vcc
	s_and_b64 vcc, s[66:67], s[4:5]
	v_cndmask_b32_e32 v51, v120, v51, vcc
	s_and_b64 vcc, s[66:67], s[6:7]
	v_cndmask_b32_e32 v52, v120, v52, vcc
	s_and_b64 vcc, s[66:67], s[8:9]
	v_cndmask_b32_e32 v53, v120, v53, vcc
	s_and_b64 vcc, s[66:67], s[14:15]
	v_cndmask_b32_e32 v54, v120, v54, vcc
	s_and_b64 vcc, s[66:67], s[16:17]
	v_cndmask_b32_e32 v55, v120, v55, vcc
	s_and_b64 vcc, s[66:67], s[18:19]
	v_cndmask_b32_e32 v56, v120, v56, vcc
	s_and_b64 vcc, s[66:67], s[20:21]
	v_cndmask_b32_e32 v57, v120, v57, vcc
	s_and_b64 vcc, s[66:67], s[22:23]
	v_cndmask_b32_e32 v58, v120, v58, vcc
	s_and_b64 vcc, s[66:67], s[24:25]
	v_cndmask_b32_e32 v59, v120, v59, vcc
	s_and_b64 vcc, s[66:67], s[26:27]
	v_cndmask_b32_e32 v60, v120, v60, vcc
	s_and_b64 vcc, s[66:67], s[28:29]
	v_cndmask_b32_e32 v61, v120, v61, vcc
	s_and_b64 vcc, s[66:67], s[30:31]
	v_cndmask_b32_e32 v62, v120, v62, vcc
	s_and_b64 vcc, s[66:67], s[34:35]
	v_cndmask_b32_e32 v63, v120, v63, vcc
	s_and_b64 vcc, s[66:67], s[36:37]
	v_cndmask_b32_e32 v32, v120, v32, vcc
	s_and_b64 vcc, s[66:67], s[12:13]
	v_max3_f32 v88, v48, s33, v49
	v_cndmask_b32_e32 v33, v120, v33, vcc
	s_and_b64 vcc, s[66:67], s[38:39]
	v_max3_f32 v88, v88, v50, v51
	v_cndmask_b32_e32 v34, v120, v34, vcc
	s_and_b64 vcc, s[66:67], s[40:41]
	v_max3_f32 v88, v88, v52, v53
	v_cndmask_b32_e32 v35, v120, v35, vcc
	s_and_b64 vcc, s[66:67], s[42:43]
	v_max3_f32 v88, v88, v54, v55
	v_cndmask_b32_e32 v36, v120, v36, vcc
	s_and_b64 vcc, s[66:67], s[44:45]
	v_max3_f32 v88, v88, v56, v57
	v_cndmask_b32_e32 v37, v120, v37, vcc
	s_and_b64 vcc, s[66:67], s[46:47]
	v_max3_f32 v88, v88, v58, v59
	v_cndmask_b32_e32 v38, v120, v38, vcc
	s_and_b64 vcc, s[66:67], s[48:49]
	v_max3_f32 v88, v88, v60, v61
	v_cndmask_b32_e32 v39, v120, v39, vcc
	s_and_b64 vcc, s[66:67], s[50:51]
	v_max3_f32 v88, v88, v62, v63
	v_cndmask_b32_e32 v40, v120, v40, vcc
	s_and_b64 vcc, s[66:67], s[52:53]
	v_max3_f32 v88, v88, v32, v33
	v_cndmask_b32_e32 v41, v120, v41, vcc
	s_and_b64 vcc, s[66:67], s[54:55]
	v_max3_f32 v88, v88, v34, v35
	v_cndmask_b32_e32 v42, v120, v42, vcc
	s_and_b64 vcc, s[66:67], s[56:57]
	v_max3_f32 v88, v88, v36, v37
	v_cndmask_b32_e32 v43, v120, v43, vcc
	s_and_b64 vcc, s[66:67], s[58:59]
	v_max3_f32 v88, v88, v38, v39
	v_cndmask_b32_e32 v44, v120, v44, vcc
	s_and_b64 vcc, s[66:67], s[60:61]
	v_max3_f32 v88, v88, v40, v41
	v_cndmask_b32_e32 v45, v120, v45, vcc
	s_and_b64 vcc, s[66:67], s[62:63]
	v_max3_f32 v88, v88, v42, v43
	v_cndmask_b32_e32 v46, v120, v46, vcc
	s_and_b64 vcc, s[66:67], s[64:65]
	v_max3_f32 v88, v88, v44, v45
	v_cndmask_b32_e32 v47, v120, v47, vcc
	v_max3_f32 v88, v88, v46, v47
	ds_bpermute_b32 v89, v113, v88
	s_waitcnt lgkmcnt(0)
	v_max3_f32 v128, v129, v88, v89
	v_sub_f32_e32 v48, v48, v128
	v_exp_f32_e32 v88, v48
	v_sub_f32_e32 v49, v49, v128
	v_exp_f32_e32 v90, v49
	v_sub_f32_e32 v49, v50, v128
	v_exp_f32_e32 v91, v49
	v_sub_f32_e32 v49, v51, v128
	v_exp_f32_e32 v92, v49
	v_sub_f32_e32 v49, v52, v128
	v_add_f32_e32 v89, 0, v88
	v_exp_f32_e32 v93, v49
	v_sub_f32_e32 v50, v53, v128
	v_add_f32_e32 v49, v90, v89
	v_exp_f32_e32 v89, v50
	v_sub_f32_e32 v50, v54, v128
	v_add_f32_e32 v49, v91, v49
	v_exp_f32_e32 v94, v50
	v_sub_f32_e32 v50, v55, v128
	v_add_f32_e32 v49, v92, v49
	v_exp_f32_e32 v95, v50
	v_sub_f32_e32 v50, v56, v128
	v_add_f32_e32 v49, v93, v49
	v_exp_f32_e32 v96, v50
	v_sub_f32_e32 v50, v57, v128
	v_add_f32_e32 v49, v89, v49
	v_exp_f32_e32 v97, v50
	v_sub_f32_e32 v50, v58, v128
	v_add_f32_e32 v49, v94, v49
	v_exp_f32_e32 v98, v50
	v_sub_f32_e32 v50, v59, v128
	v_add_f32_e32 v49, v95, v49
	v_exp_f32_e32 v99, v50
	v_sub_f32_e32 v50, v60, v128
	v_add_f32_e32 v49, v96, v49
	v_exp_f32_e32 v100, v50
	v_sub_f32_e32 v50, v61, v128
	v_add_f32_e32 v49, v97, v49
	v_exp_f32_e32 v101, v50
	v_sub_f32_e32 v50, v62, v128
	v_add_f32_e32 v49, v98, v49
	v_exp_f32_e32 v102, v50
	v_sub_f32_e32 v50, v63, v128
	v_add_f32_e32 v49, v99, v49
	v_exp_f32_e32 v103, v50
	v_sub_f32_e32 v32, v32, v128
	v_sub_f32_e32 v48, v129, v128
	v_add_f32_e32 v49, v100, v49
	v_exp_f32_e32 v129, v32
	v_sub_f32_e32 v33, v33, v128
	v_add_f32_e32 v32, v101, v49
	v_exp_f32_e32 v131, v33
	v_sub_f32_e32 v33, v34, v128
	v_add_f32_e32 v32, v102, v32
	v_exp_f32_e32 v132, v33
	v_sub_f32_e32 v33, v35, v128
	v_add_f32_e32 v32, v103, v32
	v_exp_f32_e32 v133, v33
	v_sub_f32_e32 v33, v36, v128
	v_add_f32_e32 v32, v129, v32
	v_exp_f32_e32 v134, v33
	v_sub_f32_e32 v33, v37, v128
	v_add_f32_e32 v32, v131, v32
	v_exp_f32_e32 v135, v33
	v_sub_f32_e32 v33, v38, v128
	v_add_f32_e32 v32, v132, v32
	v_exp_f32_e32 v136, v33
	v_sub_f32_e32 v33, v39, v128
	v_add_f32_e32 v32, v133, v32
	v_exp_f32_e32 v137, v33
	v_sub_f32_e32 v33, v40, v128
	v_add_f32_e32 v32, v134, v32
	v_exp_f32_e32 v138, v33
	v_sub_f32_e32 v33, v41, v128
	v_add_f32_e32 v32, v135, v32
	v_exp_f32_e32 v139, v33
	v_sub_f32_e32 v33, v42, v128
	v_add_f32_e32 v32, v136, v32
	v_exp_f32_e32 v140, v33
	v_sub_f32_e32 v33, v43, v128
	v_add_f32_e32 v32, v137, v32
	v_exp_f32_e32 v141, v33
	v_sub_f32_e32 v33, v44, v128
	v_add_f32_e32 v32, v138, v32
	v_exp_f32_e32 v142, v33
	v_add_f32_e32 v32, v139, v32
	v_add_f32_e32 v32, v140, v32
	v_add_f32_e32 v32, v141, v32
	v_add_f32_e32 v33, v142, v32
	v_sub_f32_e32 v32, v45, v128
	v_exp_f32_e32 v143, v32
	v_sub_f32_e32 v32, v46, v128
	v_exp_f32_e32 v144, v32
	v_sub_f32_e32 v32, v47, v128
	v_exp_f32_e32 v145, v32
	v_exp_f32_e32 v32, v48
	v_add_f32_e32 v33, v143, v33
	v_add_f32_e32 v33, v144, v33
	v_add_f32_e32 v130, v145, v33
	v_pk_mul_f32 v[38:39], v[6:7], v[32:33] op_sel_hi:[1,0]
	v_pk_mul_f32 v[36:37], v[4:5], v[32:33] op_sel_hi:[1,0]
	ds_read2_b64 v[4:7], v116 offset1:2
	v_fmac_f32_e32 v130, v117, v32
	v_pk_mul_f32 v[62:63], v[30:31], v[32:33] op_sel_hi:[1,0]
	v_pk_mul_f32 v[60:61], v[28:29], v[32:33] op_sel_hi:[1,0]
	v_pk_mul_f32 v[58:59], v[26:27], v[32:33] op_sel_hi:[1,0]
	v_pk_mul_f32 v[56:57], v[24:25], v[32:33] op_sel_hi:[1,0]
	v_pk_mul_f32 v[54:55], v[22:23], v[32:33] op_sel_hi:[1,0]
	v_pk_mul_f32 v[52:53], v[20:21], v[32:33] op_sel_hi:[1,0]
	v_pk_mul_f32 v[50:51], v[18:19], v[32:33] op_sel_hi:[1,0]
	v_pk_mul_f32 v[48:49], v[16:17], v[32:33] op_sel_hi:[1,0]
	v_pk_mul_f32 v[46:47], v[14:15], v[32:33] op_sel_hi:[1,0]
	v_pk_mul_f32 v[44:45], v[12:13], v[32:33] op_sel_hi:[1,0]
	v_pk_mul_f32 v[42:43], v[10:11], v[32:33] op_sel_hi:[1,0]
	v_pk_mul_f32 v[40:41], v[8:9], v[32:33] op_sel_hi:[1,0]
	v_pk_mul_f32 v[34:35], v[2:3], v[32:33] op_sel_hi:[1,0]
	v_pk_mul_f32 v[32:33], v[0:1], v[32:33] op_sel_hi:[1,0]
	v_cvt_pk_bf16_f32 v0, v88, v90
	v_cvt_pk_bf16_f32 v1, v91, v92
	v_cvt_pk_bf16_f32 v2, v93, v89
	v_cvt_pk_bf16_f32 v3, v94, v95
	ds_read2_b64 v[16:19], v116 offset0:4 offset1:6
	v_cvt_pk_bf16_f32 v8, v96, v97
	s_waitcnt lgkmcnt(1)
	v_mfma_f32_32x32x16_bf16 v[48:63], v[4:7], v[0:3], v[48:63]
	v_cvt_pk_bf16_f32 v9, v98, v99
	v_cvt_pk_bf16_f32 v10, v100, v101
	v_cvt_pk_bf16_f32 v11, v102, v103
	v_cvt_pk_bf16_f32 v12, v129, v131
	v_cvt_pk_bf16_f32 v13, v132, v133
	v_cvt_pk_bf16_f32 v14, v134, v135
	v_cvt_pk_bf16_f32 v15, v136, v137
	s_waitcnt lgkmcnt(0)
	v_mfma_f32_32x32x16_bf16 v[48:63], v[16:19], v[8:11], v[48:63]
	v_cvt_pk_bf16_f32 v4, v138, v139
	v_cvt_pk_bf16_f32 v5, v140, v141
	v_cvt_pk_bf16_f32 v6, v142, v143
	v_cvt_pk_bf16_f32 v7, v144, v145
	ds_read2_b64 v[16:19], v116 offset0:8 offset1:10
	s_waitcnt lgkmcnt(0)
	v_mfma_f32_32x32x16_bf16 v[48:63], v[16:19], v[12:15], v[48:63]
	ds_read2_b64 v[16:19], v116 offset0:12 offset1:14
	s_waitcnt lgkmcnt(0)
	v_mfma_f32_32x32x16_bf16 v[48:63], v[16:19], v[4:7], v[48:63]
	ds_read2_b64 v[16:19], v111 offset0:64 offset1:66
	s_waitcnt lgkmcnt(0)
	v_mfma_f32_32x32x16_bf16 v[32:47], v[16:19], v[0:3], v[32:47]
	ds_read2_b64 v[0:3], v111 offset0:68 offset1:70
	s_waitcnt lgkmcnt(0)
	v_mfma_f32_32x32x16_bf16 v[32:47], v[0:3], v[8:11], v[32:47]
	ds_read2_b64 v[0:3], v111 offset0:72 offset1:74
	s_waitcnt lgkmcnt(0)
	v_mfma_f32_32x32x16_bf16 v[32:47], v[0:3], v[12:15], v[32:47]
	ds_read2_b64 v[0:3], v111 offset0:76 offset1:78
	s_waitcnt lgkmcnt(0)
	v_mfma_f32_32x32x16_bf16 v[32:47], v[0:3], v[4:7], v[32:47]
	s_andn2_b64 vcc, exec, s[68:69]
	s_xor_b32 s73, s73, 1
	s_cbranch_vccz .LBB0_511
	s_branch .LBB0_512
	s_nop 0
	s_nop 0
	s_nop 0
	s_nop 0
	s_nop 0
	s_nop 0
	s_nop 0
	s_nop 0
	s_nop 0
	s_nop 0
	s_nop 0
	s_nop 0
	s_nop 0
	s_nop 0
	s_nop 0
	s_nop 0
	s_nop 0
	s_nop 0
	s_nop 0
	s_nop 0
	s_nop 0
	s_nop 0
	s_nop 0
	s_nop 0
	s_nop 0
	s_nop 0
	s_nop 0
	s_nop 0
	s_nop 0
	s_nop 0
	s_nop 0
	s_nop 0
	s_nop 0
	s_nop 0
	s_nop 0
	s_nop 0
	s_nop 0
	s_nop 0
	s_nop 0
	s_nop 0
	s_nop 0
	s_nop 0
	s_nop 0
	s_nop 0
	s_nop 0
	s_nop 0
	s_nop 0
	s_nop 0
	s_nop 0
	s_nop 0
	s_nop 0
	s_nop 0

.LBB0_577:
	s_ashr_i32 s21, s34, 31
	s_lshr_b32 s21, s21, 29
	v_lshl_add_u32 v170, s34, 8, v158
	v_lshl_or_b32 v168, s58, 8, v160
	s_add_i32 s21, s34, s21
	v_ashrrev_i32_e32 v171, 31, v170
	s_ashr_i32 s21, s21, 3
	v_ashrrev_i32_e32 v169, 31, v168
	v_lshlrev_b64 v[130:131], 10, v[170:171]
	s_mul_hi_i32 s23, s21, 0x6000
	s_mulk_i32 s21, 0x6000
	v_lshl_add_u64 v[130:131], v[130:131], 0, v[168:169]
	s_add_u32 s36, s50, s21
	v_lshlrev_b64 v[156:157], 2, v[130:131]
	s_addc_u32 s37, s51, s23
	v_lshl_add_u64 v[172:173], s[0:1], 0, v[156:157]
	v_lshl_add_u64 v[128:129], v[168:169], 2, s[36:37]
	flat_load_dwordx4 v[164:167], v[172:173]
	flat_load_dwordx4 v[140:143], v[128:129]
	v_lshl_add_u64 v[174:175], s[2:3], 0, v[156:157]
	flat_load_dwordx4 v[136:139], v[128:129] offset:64
	flat_load_dwordx4 v[132:135], v[128:129] offset:512
	s_nop 0
	flat_load_dwordx4 v[128:131], v[128:129] offset:576
	s_andn2_b64 vcc, exec, s[10:11]
	s_mov_b64 s[10:11], -1
	s_waitcnt vmcnt(0) lgkmcnt(0)
	v_pk_fma_f32 v[126:127], v[126:127], v[142:143], v[166:167]
	v_pk_fma_f32 v[124:125], v[124:125], v[140:141], v[164:165]
	global_store_dwordx4 v[174:175], v[124:127], off
	flat_load_dwordx4 v[124:127], v[172:173] offset:64
	s_waitcnt vmcnt(0) lgkmcnt(0)
	v_pk_fma_f32 v[122:123], v[122:123], v[138:139], v[126:127]
	v_pk_fma_f32 v[120:121], v[120:121], v[136:137], v[124:125]
	global_store_dwordx4 v[174:175], v[120:123], off offset:64
	flat_load_dwordx4 v[120:123], v[172:173] offset:512
	s_waitcnt vmcnt(0) lgkmcnt(0)
	v_pk_fma_f32 v[118:119], v[118:119], v[134:135], v[122:123]
	v_pk_fma_f32 v[116:117], v[116:117], v[132:133], v[120:121]
	global_store_dwordx4 v[174:175], v[116:119], off offset:512
	flat_load_dwordx4 v[116:119], v[172:173] offset:576
	v_or_b32_e32 v120, 16, v170
	v_ashrrev_i32_e32 v121, 31, v120
	v_lshlrev_b64 v[120:121], 10, v[120:121]
	v_lshl_add_u64 v[120:121], v[120:121], 0, v[168:169]
	v_lshlrev_b64 v[120:121], 2, v[120:121]
	v_lshl_add_u64 v[122:123], s[0:1], 0, v[120:121]
	s_waitcnt vmcnt(0) lgkmcnt(0)
	v_pk_fma_f32 v[106:107], v[106:107], v[130:131], v[118:119]
	v_pk_fma_f32 v[104:105], v[104:105], v[128:129], v[116:117]
	global_store_dwordx4 v[174:175], v[104:107], off offset:576
	flat_load_dwordx4 v[104:107], v[122:123]
	v_lshl_add_u64 v[116:117], s[2:3], 0, v[120:121]
	s_waitcnt vmcnt(0) lgkmcnt(0)
	v_pk_fma_f32 v[106:107], v[114:115], v[142:143], v[106:107]
	v_pk_fma_f32 v[104:105], v[112:113], v[140:141], v[104:105]
	global_store_dwordx4 v[116:117], v[104:107], off
	flat_load_dwordx4 v[104:107], v[122:123] offset:64
	s_waitcnt vmcnt(0) lgkmcnt(0)
	v_pk_fma_f32 v[106:107], v[110:111], v[138:139], v[106:107]
	v_pk_fma_f32 v[104:105], v[108:109], v[136:137], v[104:105]
	global_store_dwordx4 v[116:117], v[104:107], off offset:64
	flat_load_dwordx4 v[104:107], v[122:123] offset:512
	s_waitcnt vmcnt(0) lgkmcnt(0)
	v_pk_fma_f32 v[102:103], v[102:103], v[134:135], v[106:107]
	v_pk_fma_f32 v[100:101], v[100:101], v[132:133], v[104:105]
	global_store_dwordx4 v[116:117], v[100:103], off offset:512
	flat_load_dwordx4 v[100:103], v[122:123] offset:576
	v_or_b32_e32 v104, 32, v170
	v_ashrrev_i32_e32 v105, 31, v104
	v_lshlrev_b64 v[104:105], 10, v[104:105]
	v_lshl_add_u64 v[104:105], v[104:105], 0, v[168:169]
	v_lshlrev_b64 v[104:105], 2, v[104:105]
	v_lshl_add_u64 v[106:107], s[0:1], 0, v[104:105]
	s_waitcnt vmcnt(0) lgkmcnt(0)
	v_pk_fma_f32 v[90:91], v[90:91], v[130:131], v[102:103]
	v_pk_fma_f32 v[88:89], v[88:89], v[128:129], v[100:101]
	global_store_dwordx4 v[116:117], v[88:91], off offset:576
	flat_load_dwordx4 v[88:91], v[106:107]
	v_lshl_add_u64 v[100:101], s[2:3], 0, v[104:105]
	s_waitcnt vmcnt(0) lgkmcnt(0)
	v_pk_fma_f32 v[90:91], v[98:99], v[142:143], v[90:91]
	v_pk_fma_f32 v[88:89], v[96:97], v[140:141], v[88:89]
	global_store_dwordx4 v[100:101], v[88:91], off
	flat_load_dwordx4 v[88:91], v[106:107] offset:64
	s_waitcnt vmcnt(0) lgkmcnt(0)
	v_pk_fma_f32 v[90:91], v[94:95], v[138:139], v[90:91]
	v_pk_fma_f32 v[88:89], v[92:93], v[136:137], v[88:89]
	global_store_dwordx4 v[100:101], v[88:91], off offset:64
	flat_load_dwordx4 v[88:91], v[106:107] offset:512
	s_waitcnt vmcnt(0) lgkmcnt(0)
	v_pk_fma_f32 v[86:87], v[86:87], v[134:135], v[90:91]
	v_pk_fma_f32 v[84:85], v[84:85], v[132:133], v[88:89]
	global_store_dwordx4 v[100:101], v[84:87], off offset:512
	flat_load_dwordx4 v[84:87], v[106:107] offset:576
	v_or_b32_e32 v88, 48, v170
	v_ashrrev_i32_e32 v89, 31, v88
	v_lshlrev_b64 v[88:89], 10, v[88:89]
	v_lshl_add_u64 v[88:89], v[88:89], 0, v[168:169]
	v_lshlrev_b64 v[88:89], 2, v[88:89]
	v_lshl_add_u64 v[90:91], s[0:1], 0, v[88:89]
	s_waitcnt vmcnt(0) lgkmcnt(0)
	v_pk_fma_f32 v[74:75], v[74:75], v[130:131], v[86:87]
	v_pk_fma_f32 v[72:73], v[72:73], v[128:129], v[84:85]
	global_store_dwordx4 v[100:101], v[72:75], off offset:576
	flat_load_dwordx4 v[72:75], v[90:91]
	v_lshl_add_u64 v[84:85], s[2:3], 0, v[88:89]
	s_waitcnt vmcnt(0) lgkmcnt(0)
	v_pk_fma_f32 v[74:75], v[82:83], v[142:143], v[74:75]
	v_pk_fma_f32 v[72:73], v[80:81], v[140:141], v[72:73]
	global_store_dwordx4 v[84:85], v[72:75], off
	flat_load_dwordx4 v[72:75], v[90:91] offset:64
	s_waitcnt vmcnt(0) lgkmcnt(0)
	v_pk_fma_f32 v[74:75], v[78:79], v[138:139], v[74:75]
	v_pk_fma_f32 v[72:73], v[76:77], v[136:137], v[72:73]
	global_store_dwordx4 v[84:85], v[72:75], off offset:64
	flat_load_dwordx4 v[72:75], v[90:91] offset:512
	s_waitcnt vmcnt(0) lgkmcnt(0)
	v_pk_fma_f32 v[70:71], v[70:71], v[134:135], v[74:75]
	v_pk_fma_f32 v[68:69], v[68:69], v[132:133], v[72:73]
	global_store_dwordx4 v[84:85], v[68:71], off offset:512
	flat_load_dwordx4 v[68:71], v[90:91] offset:576
	v_lshl_add_u64 v[72:73], v[156:157], 0, s[12:13]
	v_lshl_add_u64 v[74:75], s[0:1], 0, v[72:73]
	s_waitcnt vmcnt(0) lgkmcnt(0)
	v_pk_fma_f32 v[66:67], v[66:67], v[130:131], v[70:71]
	v_pk_fma_f32 v[64:65], v[64:65], v[128:129], v[68:69]
	global_store_dwordx4 v[84:85], v[64:67], off offset:576
	flat_load_dwordx4 v[64:67], v[74:75]
	v_lshl_add_u64 v[68:69], s[2:3], 0, v[72:73]
	s_waitcnt vmcnt(0) lgkmcnt(0)
	v_pk_fma_f32 v[62:63], v[62:63], v[142:143], v[66:67]
	v_pk_fma_f32 v[60:61], v[60:61], v[140:141], v[64:65]
	global_store_dwordx4 v[68:69], v[60:63], off
	flat_load_dwordx4 v[60:63], v[74:75] offset:64
	s_waitcnt vmcnt(0) lgkmcnt(0)
	v_pk_fma_f32 v[58:59], v[58:59], v[138:139], v[62:63]
	v_pk_fma_f32 v[56:57], v[56:57], v[136:137], v[60:61]
	global_store_dwordx4 v[68:69], v[56:59], off offset:64
	flat_load_dwordx4 v[56:59], v[74:75] offset:512
	s_waitcnt vmcnt(0) lgkmcnt(0)
	v_pk_fma_f32 v[54:55], v[54:55], v[134:135], v[58:59]
	v_pk_fma_f32 v[52:53], v[52:53], v[132:133], v[56:57]
	global_store_dwordx4 v[68:69], v[52:55], off offset:512
	flat_load_dwordx4 v[52:55], v[74:75] offset:576
	v_lshl_add_u64 v[56:57], v[156:157], 0, s[14:15]
	v_lshl_add_u64 v[58:59], s[0:1], 0, v[56:57]
	s_waitcnt vmcnt(0) lgkmcnt(0)
	v_pk_fma_f32 v[42:43], v[42:43], v[130:131], v[54:55]
	v_pk_fma_f32 v[40:41], v[40:41], v[128:129], v[52:53]
	global_store_dwordx4 v[68:69], v[40:43], off offset:576
	flat_load_dwordx4 v[40:43], v[58:59]
	v_lshl_add_u64 v[52:53], s[2:3], 0, v[56:57]
	s_waitcnt vmcnt(0) lgkmcnt(0)
	v_pk_fma_f32 v[42:43], v[50:51], v[142:143], v[42:43]
	v_pk_fma_f32 v[40:41], v[48:49], v[140:141], v[40:41]
	global_store_dwordx4 v[52:53], v[40:43], off
	flat_load_dwordx4 v[40:43], v[58:59] offset:64
	s_waitcnt vmcnt(0) lgkmcnt(0)
	v_pk_fma_f32 v[42:43], v[46:47], v[138:139], v[42:43]
	v_pk_fma_f32 v[40:41], v[44:45], v[136:137], v[40:41]
	global_store_dwordx4 v[52:53], v[40:43], off offset:64
	flat_load_dwordx4 v[40:43], v[58:59] offset:512
	s_waitcnt vmcnt(0) lgkmcnt(0)
	v_pk_fma_f32 v[38:39], v[38:39], v[134:135], v[42:43]
	v_pk_fma_f32 v[36:37], v[36:37], v[132:133], v[40:41]
	global_store_dwordx4 v[52:53], v[36:39], off offset:512
	flat_load_dwordx4 v[36:39], v[58:59] offset:576
	v_lshl_add_u64 v[40:41], v[156:157], 0, s[16:17]
	v_lshl_add_u64 v[42:43], s[0:1], 0, v[40:41]
	s_waitcnt vmcnt(0) lgkmcnt(0)
	v_pk_fma_f32 v[26:27], v[26:27], v[130:131], v[38:39]
	v_pk_fma_f32 v[24:25], v[24:25], v[128:129], v[36:37]
	global_store_dwordx4 v[52:53], v[24:27], off offset:576
	flat_load_dwordx4 v[24:27], v[42:43]
	v_lshl_add_u64 v[36:37], s[2:3], 0, v[40:41]
	s_waitcnt vmcnt(0) lgkmcnt(0)
	v_pk_fma_f32 v[26:27], v[34:35], v[142:143], v[26:27]
	v_pk_fma_f32 v[24:25], v[32:33], v[140:141], v[24:25]
	global_store_dwordx4 v[36:37], v[24:27], off
	flat_load_dwordx4 v[24:27], v[42:43] offset:64
	s_waitcnt vmcnt(0) lgkmcnt(0)
	v_pk_fma_f32 v[26:27], v[30:31], v[138:139], v[26:27]
	v_pk_fma_f32 v[24:25], v[28:29], v[136:137], v[24:25]
	global_store_dwordx4 v[36:37], v[24:27], off offset:64
	flat_load_dwordx4 v[24:27], v[42:43] offset:512
	s_waitcnt vmcnt(0) lgkmcnt(0)
	v_pk_fma_f32 v[22:23], v[22:23], v[134:135], v[26:27]
	v_pk_fma_f32 v[20:21], v[20:21], v[132:133], v[24:25]
	global_store_dwordx4 v[36:37], v[20:23], off offset:512
	flat_load_dwordx4 v[20:23], v[42:43] offset:576
	v_lshl_add_u64 v[24:25], v[156:157], 0, s[18:19]
	v_lshl_add_u64 v[26:27], s[0:1], 0, v[24:25]
	s_waitcnt vmcnt(0) lgkmcnt(0)
	v_pk_fma_f32 v[10:11], v[10:11], v[130:131], v[22:23]
	v_pk_fma_f32 v[8:9], v[8:9], v[128:129], v[20:21]
	global_store_dwordx4 v[36:37], v[8:11], off offset:576
	flat_load_dwordx4 v[8:11], v[26:27]
	v_lshl_add_u64 v[20:21], s[2:3], 0, v[24:25]
	s_waitcnt vmcnt(0) lgkmcnt(0)
	v_pk_fma_f32 v[10:11], v[18:19], v[142:143], v[10:11]
	v_pk_fma_f32 v[8:9], v[16:17], v[140:141], v[8:9]
	global_store_dwordx4 v[20:21], v[8:11], off
	flat_load_dwordx4 v[8:11], v[26:27] offset:64
	s_waitcnt vmcnt(0) lgkmcnt(0)
	v_pk_fma_f32 v[10:11], v[14:15], v[138:139], v[10:11]
	v_pk_fma_f32 v[8:9], v[12:13], v[136:137], v[8:9]
	global_store_dwordx4 v[20:21], v[8:11], off offset:64
	flat_load_dwordx4 v[8:11], v[26:27] offset:512
	s_waitcnt vmcnt(0) lgkmcnt(0)
	v_pk_fma_f32 v[6:7], v[6:7], v[134:135], v[10:11]
	v_pk_fma_f32 v[4:5], v[4:5], v[132:133], v[8:9]
	global_store_dwordx4 v[20:21], v[4:7], off offset:512
	flat_load_dwordx4 v[4:7], v[26:27] offset:576
	s_waitcnt vmcnt(0) lgkmcnt(0)
	v_pk_fma_f32 v[2:3], v[2:3], v[130:131], v[6:7]
	v_pk_fma_f32 v[0:1], v[0:1], v[128:129], v[4:5]
	global_store_dwordx4 v[20:21], v[0:3], off offset:576
	s_cbranch_vccnz .LBB0_566
	s_andn2_b64 vcc, exec, s[4:5]
	s_cbranch_vccnz .LBB0_565
	s_barrier
	s_branch .LBB0_565

.LBB0_818:
	s_ashr_i32 s26, s57, 31
	s_lshr_b32 s26, s26, 29
	s_add_i32 s26, s57, s26
	s_ashr_i32 s26, s26, 3
	v_lshl_add_u32 v160, s57, 8, v162
	v_lshl_or_b32 v64, s58, 8, v164
	s_mul_hi_i32 s27, s26, 0x6000
	s_mulk_i32 s26, 0x6000
	v_ashrrev_i32_e32 v161, 31, v160
	s_add_u32 s26, s45, s26
	v_ashrrev_i32_e32 v65, 31, v64
	v_lshlrev_b64 v[156:157], 12, v[160:161]
	s_addc_u32 s27, s46, s27
	v_lshlrev_b64 v[158:159], 2, v[64:65]
	v_lshl_add_u64 v[156:157], s[2:3], 0, v[156:157]
	v_lshl_add_u64 v[64:65], s[26:27], 0, v[158:159]
	v_lshl_add_u64 v[156:157], v[156:157], 0, v[158:159]
	flat_load_dwordx4 v[128:131], v[64:65]
	flat_load_dwordx4 v[116:119], v[64:65] offset:64
	flat_load_dwordx4 v[108:111], v[64:65] offset:512
	s_nop 0
	flat_load_dwordx4 v[64:67], v[64:65] offset:576
	s_mov_b64 s[26:27], -1
	flat_load_dwordx4 v[168:171], v[156:157]
	s_waitcnt vmcnt(0) lgkmcnt(0)
	v_pk_fma_f32 v[142:143], v[142:143], v[130:131], v[170:171]
	v_pk_fma_f32 v[140:141], v[140:141], v[128:129], v[168:169]
	global_store_dwordx4 v[156:157], v[140:143], off
	flat_load_dwordx4 v[140:143], v[156:157] offset:64
	s_waitcnt vmcnt(0) lgkmcnt(0)
	v_pk_fma_f32 v[138:139], v[138:139], v[118:119], v[142:143]
	v_pk_fma_f32 v[136:137], v[136:137], v[116:117], v[140:141]
	global_store_dwordx4 v[156:157], v[136:139], off offset:64
	flat_load_dwordx4 v[136:139], v[156:157] offset:512
	s_waitcnt vmcnt(0) lgkmcnt(0)
	v_pk_fma_f32 v[134:135], v[134:135], v[110:111], v[138:139]
	v_pk_fma_f32 v[132:133], v[132:133], v[108:109], v[136:137]
	global_store_dwordx4 v[156:157], v[132:135], off offset:512
	flat_load_dwordx4 v[132:135], v[156:157] offset:576
	s_waitcnt vmcnt(0) lgkmcnt(0)
	v_pk_fma_f32 v[126:127], v[126:127], v[66:67], v[134:135]
	v_pk_fma_f32 v[124:125], v[124:125], v[64:65], v[132:133]
	global_store_dwordx4 v[156:157], v[124:127], off offset:576
	s_nop 1
	v_or_b32_e32 v124, 16, v160
	v_ashrrev_i32_e32 v125, 31, v124
	v_lshlrev_b64 v[124:125], 12, v[124:125]
	v_lshl_add_u64 v[124:125], s[2:3], 0, v[124:125]
	v_lshl_add_u64 v[132:133], v[124:125], 0, v[158:159]
	flat_load_dwordx4 v[124:127], v[132:133]
	s_waitcnt vmcnt(0) lgkmcnt(0)
	v_pk_fma_f32 v[122:123], v[122:123], v[130:131], v[126:127]
	v_pk_fma_f32 v[120:121], v[120:121], v[128:129], v[124:125]
	global_store_dwordx4 v[132:133], v[120:123], off
	flat_load_dwordx4 v[120:123], v[132:133] offset:64
	s_waitcnt vmcnt(0) lgkmcnt(0)
	v_pk_fma_f32 v[114:115], v[114:115], v[118:119], v[122:123]
	v_pk_fma_f32 v[112:113], v[112:113], v[116:117], v[120:121]
	global_store_dwordx4 v[132:133], v[112:115], off offset:64
	flat_load_dwordx4 v[112:115], v[132:133] offset:512
	s_waitcnt vmcnt(0) lgkmcnt(0)
	v_pk_fma_f32 v[106:107], v[106:107], v[110:111], v[114:115]
	v_pk_fma_f32 v[104:105], v[104:105], v[108:109], v[112:113]
	global_store_dwordx4 v[132:133], v[104:107], off offset:512
	flat_load_dwordx4 v[104:107], v[132:133] offset:576
	s_waitcnt vmcnt(0) lgkmcnt(0)
	v_pk_fma_f32 v[102:103], v[102:103], v[66:67], v[106:107]
	v_pk_fma_f32 v[100:101], v[100:101], v[64:65], v[104:105]
	global_store_dwordx4 v[132:133], v[100:103], off offset:576
	s_nop 1
	v_or_b32_e32 v100, 32, v160
	v_ashrrev_i32_e32 v101, 31, v100
	v_lshlrev_b64 v[100:101], 12, v[100:101]
	v_lshl_add_u64 v[100:101], s[2:3], 0, v[100:101]
	v_lshl_add_u64 v[104:105], v[100:101], 0, v[158:159]
	flat_load_dwordx4 v[100:103], v[104:105]
	s_waitcnt vmcnt(0) lgkmcnt(0)
	v_pk_fma_f32 v[98:99], v[98:99], v[130:131], v[102:103]
	v_pk_fma_f32 v[96:97], v[96:97], v[128:129], v[100:101]
	global_store_dwordx4 v[104:105], v[96:99], off
	flat_load_dwordx4 v[96:99], v[104:105] offset:64
	s_waitcnt vmcnt(0) lgkmcnt(0)
	v_pk_fma_f32 v[94:95], v[94:95], v[118:119], v[98:99]
	v_pk_fma_f32 v[92:93], v[92:93], v[116:117], v[96:97]
	global_store_dwordx4 v[104:105], v[92:95], off offset:64
	flat_load_dwordx4 v[92:95], v[104:105] offset:512
	s_waitcnt vmcnt(0) lgkmcnt(0)
	v_pk_fma_f32 v[90:91], v[90:91], v[110:111], v[94:95]
	v_pk_fma_f32 v[88:89], v[88:89], v[108:109], v[92:93]
	global_store_dwordx4 v[104:105], v[88:91], off offset:512
	flat_load_dwordx4 v[88:91], v[104:105] offset:576
	s_waitcnt vmcnt(0) lgkmcnt(0)
	v_pk_fma_f32 v[86:87], v[86:87], v[66:67], v[90:91]
	v_pk_fma_f32 v[84:85], v[84:85], v[64:65], v[88:89]
	global_store_dwordx4 v[104:105], v[84:87], off offset:576
	s_nop 1
	v_or_b32_e32 v84, 48, v160
	v_ashrrev_i32_e32 v85, 31, v84
	v_lshlrev_b64 v[84:85], 12, v[84:85]
	v_lshl_add_u64 v[84:85], s[2:3], 0, v[84:85]
	v_lshl_add_u64 v[88:89], v[84:85], 0, v[158:159]
	flat_load_dwordx4 v[84:87], v[88:89]
	s_waitcnt vmcnt(0) lgkmcnt(0)
	v_pk_fma_f32 v[82:83], v[82:83], v[130:131], v[86:87]
	v_pk_fma_f32 v[80:81], v[80:81], v[128:129], v[84:85]
	global_store_dwordx4 v[88:89], v[80:83], off
	flat_load_dwordx4 v[80:83], v[88:89] offset:64
	s_waitcnt vmcnt(0) lgkmcnt(0)
	v_pk_fma_f32 v[78:79], v[78:79], v[118:119], v[82:83]
	v_pk_fma_f32 v[76:77], v[76:77], v[116:117], v[80:81]
	global_store_dwordx4 v[88:89], v[76:79], off offset:64
	flat_load_dwordx4 v[76:79], v[88:89] offset:512
	s_waitcnt vmcnt(0) lgkmcnt(0)
	v_pk_fma_f32 v[74:75], v[74:75], v[110:111], v[78:79]
	v_pk_fma_f32 v[72:73], v[72:73], v[108:109], v[76:77]
	global_store_dwordx4 v[88:89], v[72:75], off offset:512
	flat_load_dwordx4 v[72:75], v[88:89] offset:576
	s_waitcnt vmcnt(0) lgkmcnt(0)
	v_pk_fma_f32 v[70:71], v[70:71], v[66:67], v[74:75]
	v_add_co_u32_e32 v74, vcc, s51, v156
	v_pk_fma_f32 v[68:69], v[68:69], v[64:65], v[72:73]
	s_nop 0
	v_addc_co_u32_e32 v75, vcc, 0, v157, vcc
	global_store_dwordx4 v[88:89], v[68:71], off offset:576
	flat_load_dwordx4 v[68:71], v[74:75]
	v_lshl_add_u64 v[72:73], v[156:157], 0, s[12:13]
	s_waitcnt vmcnt(0) lgkmcnt(0)
	v_pk_fma_f32 v[62:63], v[62:63], v[130:131], v[70:71]
	v_pk_fma_f32 v[60:61], v[60:61], v[128:129], v[68:69]
	global_store_dwordx4 v[74:75], v[60:63], off
	flat_load_dwordx4 v[60:63], v[72:73] offset:64
	s_waitcnt vmcnt(0) lgkmcnt(0)
	v_pk_fma_f32 v[58:59], v[58:59], v[118:119], v[62:63]
	v_pk_fma_f32 v[56:57], v[56:57], v[116:117], v[60:61]
	global_store_dwordx4 v[72:73], v[56:59], off offset:64
	flat_load_dwordx4 v[56:59], v[72:73] offset:512
	s_waitcnt vmcnt(0) lgkmcnt(0)
	v_pk_fma_f32 v[54:55], v[54:55], v[110:111], v[58:59]
	v_pk_fma_f32 v[52:53], v[52:53], v[108:109], v[56:57]
	global_store_dwordx4 v[72:73], v[52:55], off offset:512
	flat_load_dwordx4 v[52:55], v[72:73] offset:576
	s_waitcnt vmcnt(0) lgkmcnt(0)
	v_pk_fma_f32 v[50:51], v[50:51], v[66:67], v[54:55]
	v_add_co_u32_e32 v54, vcc, s52, v156
	v_pk_fma_f32 v[48:49], v[48:49], v[64:65], v[52:53]
	s_nop 0
	v_addc_co_u32_e32 v55, vcc, 0, v157, vcc
	global_store_dwordx4 v[72:73], v[48:51], off offset:576
	flat_load_dwordx4 v[48:51], v[54:55]
	v_lshl_add_u64 v[52:53], v[156:157], 0, s[14:15]
	s_waitcnt vmcnt(0) lgkmcnt(0)
	v_pk_fma_f32 v[46:47], v[46:47], v[130:131], v[50:51]
	v_pk_fma_f32 v[44:45], v[44:45], v[128:129], v[48:49]
	global_store_dwordx4 v[54:55], v[44:47], off
	flat_load_dwordx4 v[44:47], v[52:53] offset:64
	s_waitcnt vmcnt(0) lgkmcnt(0)
	v_pk_fma_f32 v[42:43], v[42:43], v[118:119], v[46:47]
	v_pk_fma_f32 v[40:41], v[40:41], v[116:117], v[44:45]
	global_store_dwordx4 v[52:53], v[40:43], off offset:64
	flat_load_dwordx4 v[40:43], v[52:53] offset:512
	s_waitcnt vmcnt(0) lgkmcnt(0)
	v_pk_fma_f32 v[38:39], v[38:39], v[110:111], v[42:43]
	v_pk_fma_f32 v[36:37], v[36:37], v[108:109], v[40:41]
	global_store_dwordx4 v[52:53], v[36:39], off offset:512
	flat_load_dwordx4 v[36:39], v[52:53] offset:576
	s_waitcnt vmcnt(0) lgkmcnt(0)
	v_pk_fma_f32 v[34:35], v[34:35], v[66:67], v[38:39]
	v_add_co_u32_e32 v38, vcc, s53, v156
	v_pk_fma_f32 v[32:33], v[32:33], v[64:65], v[36:37]
	s_nop 0
	v_addc_co_u32_e32 v39, vcc, 0, v157, vcc
	global_store_dwordx4 v[52:53], v[32:35], off offset:576
	flat_load_dwordx4 v[32:35], v[38:39]
	v_lshl_add_u64 v[36:37], v[156:157], 0, s[16:17]
	s_waitcnt vmcnt(0) lgkmcnt(0)
	v_pk_fma_f32 v[30:31], v[30:31], v[130:131], v[34:35]
	v_pk_fma_f32 v[28:29], v[28:29], v[128:129], v[32:33]
	global_store_dwordx4 v[38:39], v[28:31], off
	flat_load_dwordx4 v[28:31], v[36:37] offset:64
	s_waitcnt vmcnt(0) lgkmcnt(0)
	v_pk_fma_f32 v[26:27], v[26:27], v[118:119], v[30:31]
	v_pk_fma_f32 v[24:25], v[24:25], v[116:117], v[28:29]
	global_store_dwordx4 v[36:37], v[24:27], off offset:64
	flat_load_dwordx4 v[24:27], v[36:37] offset:512
	s_waitcnt vmcnt(0) lgkmcnt(0)
	v_pk_fma_f32 v[22:23], v[22:23], v[110:111], v[26:27]
	v_pk_fma_f32 v[20:21], v[20:21], v[108:109], v[24:25]
	global_store_dwordx4 v[36:37], v[20:23], off offset:512
	flat_load_dwordx4 v[20:23], v[36:37] offset:576
	s_waitcnt vmcnt(0) lgkmcnt(0)
	v_pk_fma_f32 v[18:19], v[18:19], v[66:67], v[22:23]
	v_add_co_u32_e32 v22, vcc, s54, v156
	v_pk_fma_f32 v[16:17], v[16:17], v[64:65], v[20:21]
	s_nop 0
	v_addc_co_u32_e32 v23, vcc, 0, v157, vcc
	global_store_dwordx4 v[36:37], v[16:19], off offset:576
	flat_load_dwordx4 v[18:21], v[22:23]
	s_andn2_b64 vcc, exec, s[0:1]
	v_lshl_add_u64 v[16:17], v[156:157], 0, s[4:5]
	s_waitcnt vmcnt(0) lgkmcnt(0)
	v_pk_fma_f32 v[14:15], v[14:15], v[130:131], v[20:21]
	v_pk_fma_f32 v[12:13], v[12:13], v[128:129], v[18:19]
	global_store_dwordx4 v[22:23], v[12:15], off
	flat_load_dwordx4 v[12:15], v[16:17] offset:64
	s_waitcnt vmcnt(0) lgkmcnt(0)
	v_pk_fma_f32 v[10:11], v[10:11], v[118:119], v[14:15]
	v_pk_fma_f32 v[8:9], v[8:9], v[116:117], v[12:13]
	global_store_dwordx4 v[16:17], v[8:11], off offset:64
	flat_load_dwordx4 v[8:11], v[16:17] offset:512
	s_waitcnt vmcnt(0) lgkmcnt(0)
	v_pk_fma_f32 v[6:7], v[6:7], v[110:111], v[10:11]
	v_pk_fma_f32 v[4:5], v[4:5], v[108:109], v[8:9]
	global_store_dwordx4 v[16:17], v[4:7], off offset:512
	flat_load_dwordx4 v[4:7], v[16:17] offset:576
	s_waitcnt vmcnt(0) lgkmcnt(0)
	v_pk_fma_f32 v[2:3], v[2:3], v[66:67], v[6:7]
	v_pk_fma_f32 v[0:1], v[0:1], v[64:65], v[4:5]
	global_store_dwordx4 v[16:17], v[0:3], off offset:576
	s_cbranch_vccnz .LBB0_807
	s_andn2_b64 vcc, exec, s[6:7]
	s_cbranch_vccnz .LBB0_806
	s_barrier
	s_branch .LBB0_806

	.amdhsa_kernel _Z14fwd_megakernel4Args
		.amdhsa_group_segment_fixed_size 16384
		.amdhsa_private_segment_fixed_size 0
		.amdhsa_kernarg_size 432
		.amdhsa_user_sgpr_count 2
		.amdhsa_user_sgpr_dispatch_ptr 0
		.amdhsa_user_sgpr_queue_ptr 0
		.amdhsa_user_sgpr_kernarg_segment_ptr 1
		.amdhsa_user_sgpr_dispatch_id 0
		.amdhsa_user_sgpr_kernarg_preload_length 0
		.amdhsa_user_sgpr_kernarg_preload_offset 0
		.amdhsa_user_sgpr_private_segment_size 0
		.amdhsa_uses_dynamic_stack 0
		.amdhsa_enable_private_segment 0
		.amdhsa_system_sgpr_workgroup_id_x 1
		.amdhsa_system_sgpr_workgroup_id_y 0
		.amdhsa_system_sgpr_workgroup_id_z 0
		.amdhsa_system_sgpr_workgroup_info 0
		.amdhsa_system_vgpr_workitem_id 2
		.amdhsa_next_free_vgpr 248
		.amdhsa_next_free_sgpr 102
		.amdhsa_accum_offset 248
		.amdhsa_reserve_vcc 1
		.amdhsa_float_round_mode_32 0
		.amdhsa_float_round_mode_16_64 0
		.amdhsa_float_denorm_mode_32 3
		.amdhsa_float_denorm_mode_16_64 3
		.amdhsa_dx10_clamp 1
		.amdhsa_ieee_mode 1
		.amdhsa_fp16_overflow 0
		.amdhsa_tg_split 0
		.amdhsa_exception_fp_ieee_invalid_op 0
		.amdhsa_exception_fp_denorm_src 0
		.amdhsa_exception_fp_ieee_div_zero 0
		.amdhsa_exception_fp_ieee_overflow 0
		.amdhsa_exception_fp_ieee_underflow 0
		.amdhsa_exception_fp_ieee_inexact 0
		.amdhsa_exception_int_div_zero 0
	.end_amdhsa_kernel

amdhsa.kernels:
  - .agpr_count:     0
    .args:
      - .offset:         0
        .size:           176
        .value_kind:     by_value
      - .offset:         176
        .size:           4
        .value_kind:     hidden_block_count_x
      - .offset:         180
        .size:           4
        .value_kind:     hidden_block_count_y
      - .offset:         184
        .size:           4
        .value_kind:     hidden_block_count_z
      - .offset:         188
        .size:           2
        .value_kind:     hidden_group_size_x
      - .offset:         190
        .size:           2
        .value_kind:     hidden_group_size_y
      - .offset:         192
        .size:           2
        .value_kind:     hidden_group_size_z
      - .offset:         194
        .size:           2
        .value_kind:     hidden_remainder_x
      - .offset:         196
        .size:           2
        .value_kind:     hidden_remainder_y
      - .offset:         198
        .size:           2
        .value_kind:     hidden_remainder_z
      - .offset:         216
        .size:           8
        .value_kind:     hidden_global_offset_x
      - .offset:         224
        .size:           8
        .value_kind:     hidden_global_offset_y
      - .offset:         232
        .size:           8
        .value_kind:     hidden_global_offset_z
      - .offset:         240
        .size:           2
        .value_kind:     hidden_grid_dims
      - .offset:         264
        .size:           8
        .value_kind:     hidden_multigrid_sync_arg
      - .offset:         296
        .size:           4
        .value_kind:     hidden_dynamic_lds_size
    .group_segment_fixed_size: 16384
    .kernarg_segment_align: 8
    .kernarg_segment_size: 432
    .language:       OpenCL C
    .language_version:
      - 2
      - 0
    .max_flat_workgroup_size: 512
    .name:           _Z14fwd_megakernel4Args
    .private_segment_fixed_size: 0
    .sgpr_count:     108
    .sgpr_spill_count: 120
    .symbol:         _Z14fwd_megakernel4Args.kd
    .uniform_work_group_size: 1
    .uses_dynamic_stack: false
    .vgpr_count:     248
    .vgpr_spill_count: 0
    .wavefront_size: 64
